# recurrence step 41->39 instructions: one LDS wait per step, DPP wait-state slot filled with the sa-independent v*k product of column pair 0
# baseline (speedup 1.0000x reference)
.Lrec_chunk:
	s_and_b32 s0, s4, 1
	s_mul_i32 s1, s0, 0xc000
	s_lshl_b32 s5, s0, 8
	v_add_u32_e32 v80, s1, v86
	v_add_u32_e32 v81, s1, v87
	v_add_u32_e32 v82, s1, v88
	s_add_i32 s5, s5, 0x1a100
	s_lshl_b32 s0, s0, 12
	v_mov_b32_e32 v83, s5
	v_add_u32_e32 v84, s0, v89
	ds_read_b128 v[12:15], v80 offset:768
	ds_read_b128 v[16:19], v80 offset:0
	ds_read_b128 v[20:23], v80 offset:256
	ds_read_b128 v[24:27], v80 offset:512
	ds_read_b128 v[28:31], v80 offset:1024
	ds_read_b32 v32, v81 offset:1280
	ds_read_b32 v33, v82 offset:1280
	s_waitcnt lgkmcnt(0)
	v_pk_mul_f32 v[8:9], v[0:1], v[12:13] op_sel_hi:[1,0]
	v_pk_mul_f32 v[10:11], v[0:1], v[16:17] op_sel_hi:[1,0]
	ds_read_b128 v[40:43], v80 offset:2304
	v_pk_fma_f32 v[8:9], v[2:3], v[12:13], v[8:9] op_sel:[0,1,0]
	v_pk_fma_f32 v[10:11], v[2:3], v[16:17], v[10:11] op_sel:[0,1,0]
	ds_read_b128 v[44:47], v80 offset:1536
	v_pk_fma_f32 v[8:9], v[4:5], v[14:15], v[8:9] op_sel_hi:[1,0,1]
	v_pk_fma_f32 v[10:11], v[4:5], v[18:19], v[10:11] op_sel_hi:[1,0,1]
	ds_read_b128 v[48:51], v80 offset:1792
	v_pk_fma_f32 v[8:9], v[6:7], v[14:15], v[8:9] op_sel:[0,1,0]
	v_pk_fma_f32 v[10:11], v[6:7], v[18:19], v[10:11] op_sel:[0,1,0]
	ds_read_b128 v[52:55], v80 offset:2048
	v_add_f32_dpp v74, v9, v8 row_ror:8 row_mask:0xf bank_mask:0xf bound_ctrl:1
	v_add_f32_dpp v75, v11, v10 row_ror:8 row_mask:0xf bank_mask:0xf bound_ctrl:1
	ds_read_b128 v[56:59], v80 offset:2560
	v_add_f32_dpp v74, v74, v74 quad_perm:[1,0,3,2] row_mask:0xf bank_mask:0xf bound_ctrl:1
	v_add_f32_dpp v75, v75, v75 quad_perm:[1,0,3,2] row_mask:0xf bank_mask:0xf bound_ctrl:1
	ds_read_b32 v60, v81 offset:2816
	v_add_f32_dpp v74, v74, v74 quad_perm:[2,3,0,1] row_mask:0xf bank_mask:0xf bound_ctrl:1
	v_add_f32_dpp v75, v75, v75 quad_perm:[2,3,0,1] row_mask:0xf bank_mask:0xf bound_ctrl:1
	ds_read_b32 v61, v82 offset:2816
	v_add_f32_dpp v76, v74, v74 row_half_mirror row_mask:0xf bank_mask:0xf bound_ctrl:1
	v_add_f32_dpp v36, v75, v75 row_half_mirror row_mask:0xf bank_mask:0xf bound_ctrl:1
	v_pk_mul_f32 v[66:67], v[32:33], v[24:25] op_sel_hi:[1,0]
	v_mov_b32_dpp v77, v76 row_ror:8 row_mask:0xf bank_mask:0xf bound_ctrl:1
	v_pk_mul_f32 v[68:69], v[76:77], v[28:29] op_sel:[0,1]
	v_pk_mul_f32 v[70:71], v[76:77], v[30:31] op_sel_hi:[1,0]
	v_pk_mul_f32 v[72:73], v[76:77], v[30:31] op_sel:[0,1]
	v_pk_fma_f32 v[66:67], v[76:77], v[28:29], v[66:67] op_sel_hi:[1,0,1]
	v_pk_fma_f32 v[68:69], v[32:33], v[24:25], v[68:69] op_sel:[0,1,0]
	v_pk_fma_f32 v[70:71], v[32:33], v[26:27], v[70:71] op_sel_hi:[1,0,1]
	v_pk_fma_f32 v[72:73], v[32:33], v[26:27], v[72:73] op_sel:[0,1,0]
	v_pk_fma_f32 v[0:1], v[0:1], v[20:21], v[66:67] op_sel_hi:[1,0,1]
	v_pk_fma_f32 v[2:3], v[2:3], v[20:21], v[68:69] op_sel:[0,1,0]
	v_pk_fma_f32 v[4:5], v[4:5], v[22:23], v[70:71] op_sel_hi:[1,0,1]
	v_pk_fma_f32 v[6:7], v[6:7], v[22:23], v[72:73] op_sel:[0,1,0]
	ds_write_b32 v84, v36 offset:0
	ds_write_b32 v84, v76 offset:12288
	s_waitcnt lgkmcnt(2)
	v_pk_mul_f32 v[8:9], v[0:1], v[40:41] op_sel_hi:[1,0]
	v_pk_mul_f32 v[10:11], v[0:1], v[44:45] op_sel_hi:[1,0]
	ds_read_b128 v[12:15], v80 offset:3840
	v_pk_fma_f32 v[8:9], v[2:3], v[40:41], v[8:9] op_sel:[0,1,0]
	v_pk_fma_f32 v[10:11], v[2:3], v[44:45], v[10:11] op_sel:[0,1,0]
	ds_read_b128 v[16:19], v80 offset:3072
	v_pk_fma_f32 v[8:9], v[4:5], v[42:43], v[8:9] op_sel_hi:[1,0,1]
	v_pk_fma_f32 v[10:11], v[4:5], v[46:47], v[10:11] op_sel_hi:[1,0,1]
	ds_read_b128 v[20:23], v80 offset:3328
	v_pk_fma_f32 v[8:9], v[6:7], v[42:43], v[8:9] op_sel:[0,1,0]
	v_pk_fma_f32 v[10:11], v[6:7], v[46:47], v[10:11] op_sel:[0,1,0]
	ds_read_b128 v[24:27], v80 offset:3584
	v_add_f32_dpp v74, v9, v8 row_ror:8 row_mask:0xf bank_mask:0xf bound_ctrl:1
	v_add_f32_dpp v75, v11, v10 row_ror:8 row_mask:0xf bank_mask:0xf bound_ctrl:1
	ds_read_b128 v[28:31], v80 offset:4096
	v_add_f32_dpp v74, v74, v74 quad_perm:[1,0,3,2] row_mask:0xf bank_mask:0xf bound_ctrl:1
	v_add_f32_dpp v75, v75, v75 quad_perm:[1,0,3,2] row_mask:0xf bank_mask:0xf bound_ctrl:1
	ds_read_b32 v32, v81 offset:4352
	v_add_f32_dpp v74, v74, v74 quad_perm:[2,3,0,1] row_mask:0xf bank_mask:0xf bound_ctrl:1
	v_add_f32_dpp v75, v75, v75 quad_perm:[2,3,0,1] row_mask:0xf bank_mask:0xf bound_ctrl:1
	ds_read_b32 v33, v82 offset:4352
	v_add_f32_dpp v76, v74, v74 row_half_mirror row_mask:0xf bank_mask:0xf bound_ctrl:1
	v_add_f32_dpp v64, v75, v75 row_half_mirror row_mask:0xf bank_mask:0xf bound_ctrl:1
	v_pk_mul_f32 v[66:67], v[60:61], v[52:53] op_sel_hi:[1,0]
	v_mov_b32_dpp v77, v76 row_ror:8 row_mask:0xf bank_mask:0xf bound_ctrl:1
	v_pk_mul_f32 v[68:69], v[76:77], v[56:57] op_sel:[0,1]
	v_pk_mul_f32 v[70:71], v[76:77], v[58:59] op_sel_hi:[1,0]
	v_pk_mul_f32 v[72:73], v[76:77], v[58:59] op_sel:[0,1]
	v_pk_fma_f32 v[66:67], v[76:77], v[56:57], v[66:67] op_sel_hi:[1,0,1]
	v_pk_fma_f32 v[68:69], v[60:61], v[52:53], v[68:69] op_sel:[0,1,0]
	v_pk_fma_f32 v[70:71], v[60:61], v[54:55], v[70:71] op_sel_hi:[1,0,1]
	v_pk_fma_f32 v[72:73], v[60:61], v[54:55], v[72:73] op_sel:[0,1,0]
	v_pk_fma_f32 v[0:1], v[0:1], v[48:49], v[66:67] op_sel_hi:[1,0,1]
	v_pk_fma_f32 v[2:3], v[2:3], v[48:49], v[68:69] op_sel:[0,1,0]
	v_pk_fma_f32 v[4:5], v[4:5], v[50:51], v[70:71] op_sel_hi:[1,0,1]
	v_pk_fma_f32 v[6:7], v[6:7], v[50:51], v[72:73] op_sel:[0,1,0]
	ds_write_b32 v84, v64 offset:128
	ds_write_b32 v84, v76 offset:12416
	s_waitcnt lgkmcnt(2)
	v_pk_mul_f32 v[8:9], v[0:1], v[12:13] op_sel_hi:[1,0]
	v_pk_mul_f32 v[10:11], v[0:1], v[16:17] op_sel_hi:[1,0]
	ds_read_b128 v[40:43], v80 offset:5376
	v_pk_fma_f32 v[8:9], v[2:3], v[12:13], v[8:9] op_sel:[0,1,0]
	v_pk_fma_f32 v[10:11], v[2:3], v[16:17], v[10:11] op_sel:[0,1,0]
	ds_read_b128 v[44:47], v80 offset:4608
	v_pk_fma_f32 v[8:9], v[4:5], v[14:15], v[8:9] op_sel_hi:[1,0,1]
	v_pk_fma_f32 v[10:11], v[4:5], v[18:19], v[10:11] op_sel_hi:[1,0,1]
	ds_read_b128 v[48:51], v80 offset:4864
	v_pk_fma_f32 v[8:9], v[6:7], v[14:15], v[8:9] op_sel:[0,1,0]
	v_pk_fma_f32 v[10:11], v[6:7], v[18:19], v[10:11] op_sel:[0,1,0]
	ds_read_b128 v[52:55], v80 offset:5120
	v_add_f32_dpp v74, v9, v8 row_ror:8 row_mask:0xf bank_mask:0xf bound_ctrl:1
	v_add_f32_dpp v75, v11, v10 row_ror:8 row_mask:0xf bank_mask:0xf bound_ctrl:1
	ds_read_b128 v[56:59], v80 offset:5632
	v_add_f32_dpp v74, v74, v74 quad_perm:[1,0,3,2] row_mask:0xf bank_mask:0xf bound_ctrl:1
	v_add_f32_dpp v75, v75, v75 quad_perm:[1,0,3,2] row_mask:0xf bank_mask:0xf bound_ctrl:1
	ds_read_b32 v60, v81 offset:5888
	v_add_f32_dpp v74, v74, v74 quad_perm:[2,3,0,1] row_mask:0xf bank_mask:0xf bound_ctrl:1
	v_add_f32_dpp v75, v75, v75 quad_perm:[2,3,0,1] row_mask:0xf bank_mask:0xf bound_ctrl:1
	ds_read_b32 v61, v82 offset:5888
	v_add_f32_dpp v76, v74, v74 row_half_mirror row_mask:0xf bank_mask:0xf bound_ctrl:1
	v_add_f32_dpp v36, v75, v75 row_half_mirror row_mask:0xf bank_mask:0xf bound_ctrl:1
	v_pk_mul_f32 v[66:67], v[32:33], v[24:25] op_sel_hi:[1,0]
	v_mov_b32_dpp v77, v76 row_ror:8 row_mask:0xf bank_mask:0xf bound_ctrl:1
	v_pk_mul_f32 v[68:69], v[76:77], v[28:29] op_sel:[0,1]
	v_pk_mul_f32 v[70:71], v[76:77], v[30:31] op_sel_hi:[1,0]
	v_pk_mul_f32 v[72:73], v[76:77], v[30:31] op_sel:[0,1]
	v_pk_fma_f32 v[66:67], v[76:77], v[28:29], v[66:67] op_sel_hi:[1,0,1]
	v_pk_fma_f32 v[68:69], v[32:33], v[24:25], v[68:69] op_sel:[0,1,0]
	v_pk_fma_f32 v[70:71], v[32:33], v[26:27], v[70:71] op_sel_hi:[1,0,1]
	v_pk_fma_f32 v[72:73], v[32:33], v[26:27], v[72:73] op_sel:[0,1,0]
	v_pk_fma_f32 v[0:1], v[0:1], v[20:21], v[66:67] op_sel_hi:[1,0,1]
	v_pk_fma_f32 v[2:3], v[2:3], v[20:21], v[68:69] op_sel:[0,1,0]
	v_pk_fma_f32 v[4:5], v[4:5], v[22:23], v[70:71] op_sel_hi:[1,0,1]
	v_pk_fma_f32 v[6:7], v[6:7], v[22:23], v[72:73] op_sel:[0,1,0]
	ds_write_b32 v84, v36 offset:256
	ds_write_b32 v84, v76 offset:12544
	s_waitcnt lgkmcnt(2)
	v_pk_mul_f32 v[8:9], v[0:1], v[40:41] op_sel_hi:[1,0]
	v_pk_mul_f32 v[10:11], v[0:1], v[44:45] op_sel_hi:[1,0]
	ds_read_b128 v[12:15], v80 offset:6912
	v_pk_fma_f32 v[8:9], v[2:3], v[40:41], v[8:9] op_sel:[0,1,0]
	v_pk_fma_f32 v[10:11], v[2:3], v[44:45], v[10:11] op_sel:[0,1,0]
	ds_read_b128 v[16:19], v80 offset:6144
	v_pk_fma_f32 v[8:9], v[4:5], v[42:43], v[8:9] op_sel_hi:[1,0,1]
	v_pk_fma_f32 v[10:11], v[4:5], v[46:47], v[10:11] op_sel_hi:[1,0,1]
	ds_read_b128 v[20:23], v80 offset:6400
	v_pk_fma_f32 v[8:9], v[6:7], v[42:43], v[8:9] op_sel:[0,1,0]
	v_pk_fma_f32 v[10:11], v[6:7], v[46:47], v[10:11] op_sel:[0,1,0]
	ds_read_b128 v[24:27], v80 offset:6656
	v_add_f32_dpp v74, v9, v8 row_ror:8 row_mask:0xf bank_mask:0xf bound_ctrl:1
	v_add_f32_dpp v75, v11, v10 row_ror:8 row_mask:0xf bank_mask:0xf bound_ctrl:1
	ds_read_b128 v[28:31], v80 offset:7168
	v_add_f32_dpp v74, v74, v74 quad_perm:[1,0,3,2] row_mask:0xf bank_mask:0xf bound_ctrl:1
	v_add_f32_dpp v75, v75, v75 quad_perm:[1,0,3,2] row_mask:0xf bank_mask:0xf bound_ctrl:1
	ds_read_b32 v32, v81 offset:7424
	v_add_f32_dpp v74, v74, v74 quad_perm:[2,3,0,1] row_mask:0xf bank_mask:0xf bound_ctrl:1
	v_add_f32_dpp v75, v75, v75 quad_perm:[2,3,0,1] row_mask:0xf bank_mask:0xf bound_ctrl:1
	ds_read_b32 v33, v82 offset:7424
	v_add_f32_dpp v76, v74, v74 row_half_mirror row_mask:0xf bank_mask:0xf bound_ctrl:1
	v_add_f32_dpp v64, v75, v75 row_half_mirror row_mask:0xf bank_mask:0xf bound_ctrl:1
	v_pk_mul_f32 v[66:67], v[60:61], v[52:53] op_sel_hi:[1,0]
	v_mov_b32_dpp v77, v76 row_ror:8 row_mask:0xf bank_mask:0xf bound_ctrl:1
	v_pk_mul_f32 v[68:69], v[76:77], v[56:57] op_sel:[0,1]
	v_pk_mul_f32 v[70:71], v[76:77], v[58:59] op_sel_hi:[1,0]
	v_pk_mul_f32 v[72:73], v[76:77], v[58:59] op_sel:[0,1]
	v_pk_fma_f32 v[66:67], v[76:77], v[56:57], v[66:67] op_sel_hi:[1,0,1]
	v_pk_fma_f32 v[68:69], v[60:61], v[52:53], v[68:69] op_sel:[0,1,0]
	v_pk_fma_f32 v[70:71], v[60:61], v[54:55], v[70:71] op_sel_hi:[1,0,1]
	v_pk_fma_f32 v[72:73], v[60:61], v[54:55], v[72:73] op_sel:[0,1,0]
	v_pk_fma_f32 v[0:1], v[0:1], v[48:49], v[66:67] op_sel_hi:[1,0,1]
	v_pk_fma_f32 v[2:3], v[2:3], v[48:49], v[68:69] op_sel:[0,1,0]
	v_pk_fma_f32 v[4:5], v[4:5], v[50:51], v[70:71] op_sel_hi:[1,0,1]
	v_pk_fma_f32 v[6:7], v[6:7], v[50:51], v[72:73] op_sel:[0,1,0]
	ds_write_b32 v84, v64 offset:384
	ds_write_b32 v84, v76 offset:12672
	s_waitcnt lgkmcnt(2)
	v_pk_mul_f32 v[8:9], v[0:1], v[12:13] op_sel_hi:[1,0]
	v_pk_mul_f32 v[10:11], v[0:1], v[16:17] op_sel_hi:[1,0]
	ds_read_b128 v[40:43], v80 offset:8448
	v_pk_fma_f32 v[8:9], v[2:3], v[12:13], v[8:9] op_sel:[0,1,0]
	v_pk_fma_f32 v[10:11], v[2:3], v[16:17], v[10:11] op_sel:[0,1,0]
	ds_read_b128 v[44:47], v80 offset:7680
	v_pk_fma_f32 v[8:9], v[4:5], v[14:15], v[8:9] op_sel_hi:[1,0,1]
	v_pk_fma_f32 v[10:11], v[4:5], v[18:19], v[10:11] op_sel_hi:[1,0,1]
	ds_read_b128 v[48:51], v80 offset:7936
	v_pk_fma_f32 v[8:9], v[6:7], v[14:15], v[8:9] op_sel:[0,1,0]
	v_pk_fma_f32 v[10:11], v[6:7], v[18:19], v[10:11] op_sel:[0,1,0]
	ds_read_b128 v[52:55], v80 offset:8192
	v_add_f32_dpp v74, v9, v8 row_ror:8 row_mask:0xf bank_mask:0xf bound_ctrl:1
	v_add_f32_dpp v75, v11, v10 row_ror:8 row_mask:0xf bank_mask:0xf bound_ctrl:1
	ds_read_b128 v[56:59], v80 offset:8704
	v_add_f32_dpp v74, v74, v74 quad_perm:[1,0,3,2] row_mask:0xf bank_mask:0xf bound_ctrl:1
	v_add_f32_dpp v75, v75, v75 quad_perm:[1,0,3,2] row_mask:0xf bank_mask:0xf bound_ctrl:1
	ds_read_b32 v60, v81 offset:8960
	v_add_f32_dpp v74, v74, v74 quad_perm:[2,3,0,1] row_mask:0xf bank_mask:0xf bound_ctrl:1
	v_add_f32_dpp v75, v75, v75 quad_perm:[2,3,0,1] row_mask:0xf bank_mask:0xf bound_ctrl:1
	ds_read_b32 v61, v82 offset:8960
	v_add_f32_dpp v76, v74, v74 row_half_mirror row_mask:0xf bank_mask:0xf bound_ctrl:1
	v_add_f32_dpp v36, v75, v75 row_half_mirror row_mask:0xf bank_mask:0xf bound_ctrl:1
	v_pk_mul_f32 v[66:67], v[32:33], v[24:25] op_sel_hi:[1,0]
	v_mov_b32_dpp v77, v76 row_ror:8 row_mask:0xf bank_mask:0xf bound_ctrl:1
	v_pk_mul_f32 v[68:69], v[76:77], v[28:29] op_sel:[0,1]
	v_pk_mul_f32 v[70:71], v[76:77], v[30:31] op_sel_hi:[1,0]
	v_pk_mul_f32 v[72:73], v[76:77], v[30:31] op_sel:[0,1]
	v_pk_fma_f32 v[66:67], v[76:77], v[28:29], v[66:67] op_sel_hi:[1,0,1]
	v_pk_fma_f32 v[68:69], v[32:33], v[24:25], v[68:69] op_sel:[0,1,0]
	v_pk_fma_f32 v[70:71], v[32:33], v[26:27], v[70:71] op_sel_hi:[1,0,1]
	v_pk_fma_f32 v[72:73], v[32:33], v[26:27], v[72:73] op_sel:[0,1,0]
	v_pk_fma_f32 v[0:1], v[0:1], v[20:21], v[66:67] op_sel_hi:[1,0,1]
	v_pk_fma_f32 v[2:3], v[2:3], v[20:21], v[68:69] op_sel:[0,1,0]
	v_pk_fma_f32 v[4:5], v[4:5], v[22:23], v[70:71] op_sel_hi:[1,0,1]
	v_pk_fma_f32 v[6:7], v[6:7], v[22:23], v[72:73] op_sel:[0,1,0]
	ds_write_b32 v84, v36 offset:512
	ds_write_b32 v84, v76 offset:12800
	s_waitcnt lgkmcnt(2)
	v_pk_mul_f32 v[8:9], v[0:1], v[40:41] op_sel_hi:[1,0]
	v_pk_mul_f32 v[10:11], v[0:1], v[44:45] op_sel_hi:[1,0]
	ds_read_b128 v[12:15], v80 offset:9984
	v_pk_fma_f32 v[8:9], v[2:3], v[40:41], v[8:9] op_sel:[0,1,0]
	v_pk_fma_f32 v[10:11], v[2:3], v[44:45], v[10:11] op_sel:[0,1,0]
	ds_read_b128 v[16:19], v80 offset:9216
	v_pk_fma_f32 v[8:9], v[4:5], v[42:43], v[8:9] op_sel_hi:[1,0,1]
	v_pk_fma_f32 v[10:11], v[4:5], v[46:47], v[10:11] op_sel_hi:[1,0,1]
	ds_read_b128 v[20:23], v80 offset:9472
	v_pk_fma_f32 v[8:9], v[6:7], v[42:43], v[8:9] op_sel:[0,1,0]
	v_pk_fma_f32 v[10:11], v[6:7], v[46:47], v[10:11] op_sel:[0,1,0]
	ds_read_b128 v[24:27], v80 offset:9728
	v_add_f32_dpp v74, v9, v8 row_ror:8 row_mask:0xf bank_mask:0xf bound_ctrl:1
	v_add_f32_dpp v75, v11, v10 row_ror:8 row_mask:0xf bank_mask:0xf bound_ctrl:1
	ds_read_b128 v[28:31], v80 offset:10240
	v_add_f32_dpp v74, v74, v74 quad_perm:[1,0,3,2] row_mask:0xf bank_mask:0xf bound_ctrl:1
	v_add_f32_dpp v75, v75, v75 quad_perm:[1,0,3,2] row_mask:0xf bank_mask:0xf bound_ctrl:1
	ds_read_b32 v32, v81 offset:10496
	v_add_f32_dpp v74, v74, v74 quad_perm:[2,3,0,1] row_mask:0xf bank_mask:0xf bound_ctrl:1
	v_add_f32_dpp v75, v75, v75 quad_perm:[2,3,0,1] row_mask:0xf bank_mask:0xf bound_ctrl:1
	ds_read_b32 v33, v82 offset:10496
	v_add_f32_dpp v76, v74, v74 row_half_mirror row_mask:0xf bank_mask:0xf bound_ctrl:1
	v_add_f32_dpp v64, v75, v75 row_half_mirror row_mask:0xf bank_mask:0xf bound_ctrl:1
	v_pk_mul_f32 v[66:67], v[60:61], v[52:53] op_sel_hi:[1,0]
	v_mov_b32_dpp v77, v76 row_ror:8 row_mask:0xf bank_mask:0xf bound_ctrl:1
	v_pk_mul_f32 v[68:69], v[76:77], v[56:57] op_sel:[0,1]
	v_pk_mul_f32 v[70:71], v[76:77], v[58:59] op_sel_hi:[1,0]
	v_pk_mul_f32 v[72:73], v[76:77], v[58:59] op_sel:[0,1]
	v_pk_fma_f32 v[66:67], v[76:77], v[56:57], v[66:67] op_sel_hi:[1,0,1]
	v_pk_fma_f32 v[68:69], v[60:61], v[52:53], v[68:69] op_sel:[0,1,0]
	v_pk_fma_f32 v[70:71], v[60:61], v[54:55], v[70:71] op_sel_hi:[1,0,1]
	v_pk_fma_f32 v[72:73], v[60:61], v[54:55], v[72:73] op_sel:[0,1,0]
	v_pk_fma_f32 v[0:1], v[0:1], v[48:49], v[66:67] op_sel_hi:[1,0,1]
	v_pk_fma_f32 v[2:3], v[2:3], v[48:49], v[68:69] op_sel:[0,1,0]
	v_pk_fma_f32 v[4:5], v[4:5], v[50:51], v[70:71] op_sel_hi:[1,0,1]
	v_pk_fma_f32 v[6:7], v[6:7], v[50:51], v[72:73] op_sel:[0,1,0]
	ds_write_b32 v84, v64 offset:640
	ds_write_b32 v84, v76 offset:12928
	s_waitcnt lgkmcnt(2)
	v_pk_mul_f32 v[8:9], v[0:1], v[12:13] op_sel_hi:[1,0]
	v_pk_mul_f32 v[10:11], v[0:1], v[16:17] op_sel_hi:[1,0]
	ds_read_b128 v[40:43], v80 offset:11520
	v_pk_fma_f32 v[8:9], v[2:3], v[12:13], v[8:9] op_sel:[0,1,0]
	v_pk_fma_f32 v[10:11], v[2:3], v[16:17], v[10:11] op_sel:[0,1,0]
	ds_read_b128 v[44:47], v80 offset:10752
	v_pk_fma_f32 v[8:9], v[4:5], v[14:15], v[8:9] op_sel_hi:[1,0,1]
	v_pk_fma_f32 v[10:11], v[4:5], v[18:19], v[10:11] op_sel_hi:[1,0,1]
	ds_read_b128 v[48:51], v80 offset:11008
	v_pk_fma_f32 v[8:9], v[6:7], v[14:15], v[8:9] op_sel:[0,1,0]
	v_pk_fma_f32 v[10:11], v[6:7], v[18:19], v[10:11] op_sel:[0,1,0]
	ds_read_b128 v[52:55], v80 offset:11264
	v_add_f32_dpp v74, v9, v8 row_ror:8 row_mask:0xf bank_mask:0xf bound_ctrl:1
	v_add_f32_dpp v75, v11, v10 row_ror:8 row_mask:0xf bank_mask:0xf bound_ctrl:1
	ds_read_b128 v[56:59], v80 offset:11776
	v_add_f32_dpp v74, v74, v74 quad_perm:[1,0,3,2] row_mask:0xf bank_mask:0xf bound_ctrl:1
	v_add_f32_dpp v75, v75, v75 quad_perm:[1,0,3,2] row_mask:0xf bank_mask:0xf bound_ctrl:1
	ds_read_b32 v60, v81 offset:12032
	v_add_f32_dpp v74, v74, v74 quad_perm:[2,3,0,1] row_mask:0xf bank_mask:0xf bound_ctrl:1
	v_add_f32_dpp v75, v75, v75 quad_perm:[2,3,0,1] row_mask:0xf bank_mask:0xf bound_ctrl:1
	ds_read_b32 v61, v82 offset:12032
	v_add_f32_dpp v76, v74, v74 row_half_mirror row_mask:0xf bank_mask:0xf bound_ctrl:1
	v_add_f32_dpp v36, v75, v75 row_half_mirror row_mask:0xf bank_mask:0xf bound_ctrl:1
	v_pk_mul_f32 v[66:67], v[32:33], v[24:25] op_sel_hi:[1,0]
	v_mov_b32_dpp v77, v76 row_ror:8 row_mask:0xf bank_mask:0xf bound_ctrl:1
	v_pk_mul_f32 v[68:69], v[76:77], v[28:29] op_sel:[0,1]
	v_pk_mul_f32 v[70:71], v[76:77], v[30:31] op_sel_hi:[1,0]
	v_pk_mul_f32 v[72:73], v[76:77], v[30:31] op_sel:[0,1]
	v_pk_fma_f32 v[66:67], v[76:77], v[28:29], v[66:67] op_sel_hi:[1,0,1]
	v_pk_fma_f32 v[68:69], v[32:33], v[24:25], v[68:69] op_sel:[0,1,0]
	v_pk_fma_f32 v[70:71], v[32:33], v[26:27], v[70:71] op_sel_hi:[1,0,1]
	v_pk_fma_f32 v[72:73], v[32:33], v[26:27], v[72:73] op_sel:[0,1,0]
	v_pk_fma_f32 v[0:1], v[0:1], v[20:21], v[66:67] op_sel_hi:[1,0,1]
	v_pk_fma_f32 v[2:3], v[2:3], v[20:21], v[68:69] op_sel:[0,1,0]
	v_pk_fma_f32 v[4:5], v[4:5], v[22:23], v[70:71] op_sel_hi:[1,0,1]
	v_pk_fma_f32 v[6:7], v[6:7], v[22:23], v[72:73] op_sel:[0,1,0]
	ds_write_b32 v84, v36 offset:768
	ds_write_b32 v84, v76 offset:13056
	s_waitcnt lgkmcnt(2)
	v_pk_mul_f32 v[8:9], v[0:1], v[40:41] op_sel_hi:[1,0]
	v_pk_mul_f32 v[10:11], v[0:1], v[44:45] op_sel_hi:[1,0]
	ds_read_b128 v[12:15], v80 offset:13056
	v_pk_fma_f32 v[8:9], v[2:3], v[40:41], v[8:9] op_sel:[0,1,0]
	v_pk_fma_f32 v[10:11], v[2:3], v[44:45], v[10:11] op_sel:[0,1,0]
	ds_read_b128 v[16:19], v80 offset:12288
	v_pk_fma_f32 v[8:9], v[4:5], v[42:43], v[8:9] op_sel_hi:[1,0,1]
	v_pk_fma_f32 v[10:11], v[4:5], v[46:47], v[10:11] op_sel_hi:[1,0,1]
	ds_read_b128 v[20:23], v80 offset:12544
	v_pk_fma_f32 v[8:9], v[6:7], v[42:43], v[8:9] op_sel:[0,1,0]
	v_pk_fma_f32 v[10:11], v[6:7], v[46:47], v[10:11] op_sel:[0,1,0]
	ds_read_b128 v[24:27], v80 offset:12800
	v_add_f32_dpp v74, v9, v8 row_ror:8 row_mask:0xf bank_mask:0xf bound_ctrl:1
	v_add_f32_dpp v75, v11, v10 row_ror:8 row_mask:0xf bank_mask:0xf bound_ctrl:1
	ds_read_b128 v[28:31], v80 offset:13312
	v_add_f32_dpp v74, v74, v74 quad_perm:[1,0,3,2] row_mask:0xf bank_mask:0xf bound_ctrl:1
	v_add_f32_dpp v75, v75, v75 quad_perm:[1,0,3,2] row_mask:0xf bank_mask:0xf bound_ctrl:1
	ds_read_b32 v32, v81 offset:13568
	v_add_f32_dpp v74, v74, v74 quad_perm:[2,3,0,1] row_mask:0xf bank_mask:0xf bound_ctrl:1
	v_add_f32_dpp v75, v75, v75 quad_perm:[2,3,0,1] row_mask:0xf bank_mask:0xf bound_ctrl:1
	ds_read_b32 v33, v82 offset:13568
	v_add_f32_dpp v76, v74, v74 row_half_mirror row_mask:0xf bank_mask:0xf bound_ctrl:1
	v_add_f32_dpp v64, v75, v75 row_half_mirror row_mask:0xf bank_mask:0xf bound_ctrl:1
	v_pk_mul_f32 v[66:67], v[60:61], v[52:53] op_sel_hi:[1,0]
	v_mov_b32_dpp v77, v76 row_ror:8 row_mask:0xf bank_mask:0xf bound_ctrl:1
	v_pk_mul_f32 v[68:69], v[76:77], v[56:57] op_sel:[0,1]
	v_pk_mul_f32 v[70:71], v[76:77], v[58:59] op_sel_hi:[1,0]
	v_pk_mul_f32 v[72:73], v[76:77], v[58:59] op_sel:[0,1]
	v_pk_fma_f32 v[66:67], v[76:77], v[56:57], v[66:67] op_sel_hi:[1,0,1]
	v_pk_fma_f32 v[68:69], v[60:61], v[52:53], v[68:69] op_sel:[0,1,0]
	v_pk_fma_f32 v[70:71], v[60:61], v[54:55], v[70:71] op_sel_hi:[1,0,1]
	v_pk_fma_f32 v[72:73], v[60:61], v[54:55], v[72:73] op_sel:[0,1,0]
	v_pk_fma_f32 v[0:1], v[0:1], v[48:49], v[66:67] op_sel_hi:[1,0,1]
	v_pk_fma_f32 v[2:3], v[2:3], v[48:49], v[68:69] op_sel:[0,1,0]
	v_pk_fma_f32 v[4:5], v[4:5], v[50:51], v[70:71] op_sel_hi:[1,0,1]
	v_pk_fma_f32 v[6:7], v[6:7], v[50:51], v[72:73] op_sel:[0,1,0]
	ds_write_b32 v84, v64 offset:896
	ds_write_b32 v84, v76 offset:13184
	s_waitcnt lgkmcnt(2)
	v_pk_mul_f32 v[8:9], v[0:1], v[12:13] op_sel_hi:[1,0]
	v_pk_mul_f32 v[10:11], v[0:1], v[16:17] op_sel_hi:[1,0]
	ds_read_b128 v[40:43], v80 offset:14592
	v_pk_fma_f32 v[8:9], v[2:3], v[12:13], v[8:9] op_sel:[0,1,0]
	v_pk_fma_f32 v[10:11], v[2:3], v[16:17], v[10:11] op_sel:[0,1,0]
	ds_read_b128 v[44:47], v80 offset:13824
	v_pk_fma_f32 v[8:9], v[4:5], v[14:15], v[8:9] op_sel_hi:[1,0,1]
	v_pk_fma_f32 v[10:11], v[4:5], v[18:19], v[10:11] op_sel_hi:[1,0,1]
	ds_read_b128 v[48:51], v80 offset:14080
	v_pk_fma_f32 v[8:9], v[6:7], v[14:15], v[8:9] op_sel:[0,1,0]
	v_pk_fma_f32 v[10:11], v[6:7], v[18:19], v[10:11] op_sel:[0,1,0]
	ds_read_b128 v[52:55], v80 offset:14336
	v_add_f32_dpp v74, v9, v8 row_ror:8 row_mask:0xf bank_mask:0xf bound_ctrl:1
	v_add_f32_dpp v75, v11, v10 row_ror:8 row_mask:0xf bank_mask:0xf bound_ctrl:1
	ds_read_b128 v[56:59], v80 offset:14848
	v_add_f32_dpp v74, v74, v74 quad_perm:[1,0,3,2] row_mask:0xf bank_mask:0xf bound_ctrl:1
	v_add_f32_dpp v75, v75, v75 quad_perm:[1,0,3,2] row_mask:0xf bank_mask:0xf bound_ctrl:1
	ds_read_b32 v60, v81 offset:15104
	v_add_f32_dpp v74, v74, v74 quad_perm:[2,3,0,1] row_mask:0xf bank_mask:0xf bound_ctrl:1
	v_add_f32_dpp v75, v75, v75 quad_perm:[2,3,0,1] row_mask:0xf bank_mask:0xf bound_ctrl:1
	ds_read_b32 v61, v82 offset:15104
	v_add_f32_dpp v76, v74, v74 row_half_mirror row_mask:0xf bank_mask:0xf bound_ctrl:1
	v_add_f32_dpp v36, v75, v75 row_half_mirror row_mask:0xf bank_mask:0xf bound_ctrl:1
	v_pk_mul_f32 v[66:67], v[32:33], v[24:25] op_sel_hi:[1,0]
	v_mov_b32_dpp v77, v76 row_ror:8 row_mask:0xf bank_mask:0xf bound_ctrl:1
	v_pk_mul_f32 v[68:69], v[76:77], v[28:29] op_sel:[0,1]
	v_pk_mul_f32 v[70:71], v[76:77], v[30:31] op_sel_hi:[1,0]
	v_pk_mul_f32 v[72:73], v[76:77], v[30:31] op_sel:[0,1]
	v_pk_fma_f32 v[66:67], v[76:77], v[28:29], v[66:67] op_sel_hi:[1,0,1]
	v_pk_fma_f32 v[68:69], v[32:33], v[24:25], v[68:69] op_sel:[0,1,0]
	v_pk_fma_f32 v[70:71], v[32:33], v[26:27], v[70:71] op_sel_hi:[1,0,1]
	v_pk_fma_f32 v[72:73], v[32:33], v[26:27], v[72:73] op_sel:[0,1,0]
	v_pk_fma_f32 v[0:1], v[0:1], v[20:21], v[66:67] op_sel_hi:[1,0,1]
	v_pk_fma_f32 v[2:3], v[2:3], v[20:21], v[68:69] op_sel:[0,1,0]
	v_pk_fma_f32 v[4:5], v[4:5], v[22:23], v[70:71] op_sel_hi:[1,0,1]
	v_pk_fma_f32 v[6:7], v[6:7], v[22:23], v[72:73] op_sel:[0,1,0]
	ds_write_b32 v84, v36 offset:1024
	ds_write_b32 v84, v76 offset:13312
	s_waitcnt lgkmcnt(2)
	v_pk_mul_f32 v[8:9], v[0:1], v[40:41] op_sel_hi:[1,0]
	v_pk_mul_f32 v[10:11], v[0:1], v[44:45] op_sel_hi:[1,0]
	ds_read_b128 v[12:15], v80 offset:16128
	v_pk_fma_f32 v[8:9], v[2:3], v[40:41], v[8:9] op_sel:[0,1,0]
	v_pk_fma_f32 v[10:11], v[2:3], v[44:45], v[10:11] op_sel:[0,1,0]
	ds_read_b128 v[16:19], v80 offset:15360
	v_pk_fma_f32 v[8:9], v[4:5], v[42:43], v[8:9] op_sel_hi:[1,0,1]
	v_pk_fma_f32 v[10:11], v[4:5], v[46:47], v[10:11] op_sel_hi:[1,0,1]
	ds_read_b128 v[20:23], v80 offset:15616
	v_pk_fma_f32 v[8:9], v[6:7], v[42:43], v[8:9] op_sel:[0,1,0]
	v_pk_fma_f32 v[10:11], v[6:7], v[46:47], v[10:11] op_sel:[0,1,0]
	ds_read_b128 v[24:27], v80 offset:15872
	v_add_f32_dpp v74, v9, v8 row_ror:8 row_mask:0xf bank_mask:0xf bound_ctrl:1
	v_add_f32_dpp v75, v11, v10 row_ror:8 row_mask:0xf bank_mask:0xf bound_ctrl:1
	ds_read_b128 v[28:31], v80 offset:16384
	v_add_f32_dpp v74, v74, v74 quad_perm:[1,0,3,2] row_mask:0xf bank_mask:0xf bound_ctrl:1
	v_add_f32_dpp v75, v75, v75 quad_perm:[1,0,3,2] row_mask:0xf bank_mask:0xf bound_ctrl:1
	ds_read_b32 v32, v81 offset:16640
	v_add_f32_dpp v74, v74, v74 quad_perm:[2,3,0,1] row_mask:0xf bank_mask:0xf bound_ctrl:1
	v_add_f32_dpp v75, v75, v75 quad_perm:[2,3,0,1] row_mask:0xf bank_mask:0xf bound_ctrl:1
	ds_read_b32 v33, v82 offset:16640
	v_add_f32_dpp v76, v74, v74 row_half_mirror row_mask:0xf bank_mask:0xf bound_ctrl:1
	v_add_f32_dpp v64, v75, v75 row_half_mirror row_mask:0xf bank_mask:0xf bound_ctrl:1
	v_pk_mul_f32 v[66:67], v[60:61], v[52:53] op_sel_hi:[1,0]
	v_mov_b32_dpp v77, v76 row_ror:8 row_mask:0xf bank_mask:0xf bound_ctrl:1
	v_pk_mul_f32 v[68:69], v[76:77], v[56:57] op_sel:[0,1]
	v_pk_mul_f32 v[70:71], v[76:77], v[58:59] op_sel_hi:[1,0]
	v_pk_mul_f32 v[72:73], v[76:77], v[58:59] op_sel:[0,1]
	v_pk_fma_f32 v[66:67], v[76:77], v[56:57], v[66:67] op_sel_hi:[1,0,1]
	v_pk_fma_f32 v[68:69], v[60:61], v[52:53], v[68:69] op_sel:[0,1,0]
	v_pk_fma_f32 v[70:71], v[60:61], v[54:55], v[70:71] op_sel_hi:[1,0,1]
	v_pk_fma_f32 v[72:73], v[60:61], v[54:55], v[72:73] op_sel:[0,1,0]
	v_pk_fma_f32 v[0:1], v[0:1], v[48:49], v[66:67] op_sel_hi:[1,0,1]
	v_pk_fma_f32 v[2:3], v[2:3], v[48:49], v[68:69] op_sel:[0,1,0]
	v_pk_fma_f32 v[4:5], v[4:5], v[50:51], v[70:71] op_sel_hi:[1,0,1]
	v_pk_fma_f32 v[6:7], v[6:7], v[50:51], v[72:73] op_sel:[0,1,0]
	ds_write_b32 v84, v64 offset:1152
	ds_write_b32 v84, v76 offset:13440
	s_waitcnt lgkmcnt(2)
	v_pk_mul_f32 v[8:9], v[0:1], v[12:13] op_sel_hi:[1,0]
	v_pk_mul_f32 v[10:11], v[0:1], v[16:17] op_sel_hi:[1,0]
	ds_read_b128 v[40:43], v80 offset:17664
	v_pk_fma_f32 v[8:9], v[2:3], v[12:13], v[8:9] op_sel:[0,1,0]
	v_pk_fma_f32 v[10:11], v[2:3], v[16:17], v[10:11] op_sel:[0,1,0]
	ds_read_b128 v[44:47], v80 offset:16896
	v_pk_fma_f32 v[8:9], v[4:5], v[14:15], v[8:9] op_sel_hi:[1,0,1]
	v_pk_fma_f32 v[10:11], v[4:5], v[18:19], v[10:11] op_sel_hi:[1,0,1]
	ds_read_b128 v[48:51], v80 offset:17152
	v_pk_fma_f32 v[8:9], v[6:7], v[14:15], v[8:9] op_sel:[0,1,0]
	v_pk_fma_f32 v[10:11], v[6:7], v[18:19], v[10:11] op_sel:[0,1,0]
	ds_read_b128 v[52:55], v80 offset:17408
	v_add_f32_dpp v74, v9, v8 row_ror:8 row_mask:0xf bank_mask:0xf bound_ctrl:1
	v_add_f32_dpp v75, v11, v10 row_ror:8 row_mask:0xf bank_mask:0xf bound_ctrl:1
	ds_read_b128 v[56:59], v80 offset:17920
	v_add_f32_dpp v74, v74, v74 quad_perm:[1,0,3,2] row_mask:0xf bank_mask:0xf bound_ctrl:1
	v_add_f32_dpp v75, v75, v75 quad_perm:[1,0,3,2] row_mask:0xf bank_mask:0xf bound_ctrl:1
	ds_read_b32 v60, v81 offset:18176
	v_add_f32_dpp v74, v74, v74 quad_perm:[2,3,0,1] row_mask:0xf bank_mask:0xf bound_ctrl:1
	v_add_f32_dpp v75, v75, v75 quad_perm:[2,3,0,1] row_mask:0xf bank_mask:0xf bound_ctrl:1
	ds_read_b32 v61, v82 offset:18176
	v_add_f32_dpp v76, v74, v74 row_half_mirror row_mask:0xf bank_mask:0xf bound_ctrl:1
	v_add_f32_dpp v36, v75, v75 row_half_mirror row_mask:0xf bank_mask:0xf bound_ctrl:1
	v_pk_mul_f32 v[66:67], v[32:33], v[24:25] op_sel_hi:[1,0]
	v_mov_b32_dpp v77, v76 row_ror:8 row_mask:0xf bank_mask:0xf bound_ctrl:1
	v_pk_mul_f32 v[68:69], v[76:77], v[28:29] op_sel:[0,1]
	v_pk_mul_f32 v[70:71], v[76:77], v[30:31] op_sel_hi:[1,0]
	v_pk_mul_f32 v[72:73], v[76:77], v[30:31] op_sel:[0,1]
	v_pk_fma_f32 v[66:67], v[76:77], v[28:29], v[66:67] op_sel_hi:[1,0,1]
	v_pk_fma_f32 v[68:69], v[32:33], v[24:25], v[68:69] op_sel:[0,1,0]
	v_pk_fma_f32 v[70:71], v[32:33], v[26:27], v[70:71] op_sel_hi:[1,0,1]
	v_pk_fma_f32 v[72:73], v[32:33], v[26:27], v[72:73] op_sel:[0,1,0]
	v_pk_fma_f32 v[0:1], v[0:1], v[20:21], v[66:67] op_sel_hi:[1,0,1]
	v_pk_fma_f32 v[2:3], v[2:3], v[20:21], v[68:69] op_sel:[0,1,0]
	v_pk_fma_f32 v[4:5], v[4:5], v[22:23], v[70:71] op_sel_hi:[1,0,1]
	v_pk_fma_f32 v[6:7], v[6:7], v[22:23], v[72:73] op_sel:[0,1,0]
	ds_write_b32 v84, v36 offset:1280
	ds_write_b32 v84, v76 offset:13568
	s_waitcnt lgkmcnt(2)
	v_pk_mul_f32 v[8:9], v[0:1], v[40:41] op_sel_hi:[1,0]
	v_pk_mul_f32 v[10:11], v[0:1], v[44:45] op_sel_hi:[1,0]
	ds_read_b128 v[12:15], v80 offset:19200
	v_pk_fma_f32 v[8:9], v[2:3], v[40:41], v[8:9] op_sel:[0,1,0]
	v_pk_fma_f32 v[10:11], v[2:3], v[44:45], v[10:11] op_sel:[0,1,0]
	ds_read_b128 v[16:19], v80 offset:18432
	v_pk_fma_f32 v[8:9], v[4:5], v[42:43], v[8:9] op_sel_hi:[1,0,1]
	v_pk_fma_f32 v[10:11], v[4:5], v[46:47], v[10:11] op_sel_hi:[1,0,1]
	ds_read_b128 v[20:23], v80 offset:18688
	v_pk_fma_f32 v[8:9], v[6:7], v[42:43], v[8:9] op_sel:[0,1,0]
	v_pk_fma_f32 v[10:11], v[6:7], v[46:47], v[10:11] op_sel:[0,1,0]
	ds_read_b128 v[24:27], v80 offset:18944
	v_add_f32_dpp v74, v9, v8 row_ror:8 row_mask:0xf bank_mask:0xf bound_ctrl:1
	v_add_f32_dpp v75, v11, v10 row_ror:8 row_mask:0xf bank_mask:0xf bound_ctrl:1
	ds_read_b128 v[28:31], v80 offset:19456
	v_add_f32_dpp v74, v74, v74 quad_perm:[1,0,3,2] row_mask:0xf bank_mask:0xf bound_ctrl:1
	v_add_f32_dpp v75, v75, v75 quad_perm:[1,0,3,2] row_mask:0xf bank_mask:0xf bound_ctrl:1
	ds_read_b32 v32, v81 offset:19712
	v_add_f32_dpp v74, v74, v74 quad_perm:[2,3,0,1] row_mask:0xf bank_mask:0xf bound_ctrl:1
	v_add_f32_dpp v75, v75, v75 quad_perm:[2,3,0,1] row_mask:0xf bank_mask:0xf bound_ctrl:1
	ds_read_b32 v33, v82 offset:19712
	v_add_f32_dpp v76, v74, v74 row_half_mirror row_mask:0xf bank_mask:0xf bound_ctrl:1
	v_add_f32_dpp v64, v75, v75 row_half_mirror row_mask:0xf bank_mask:0xf bound_ctrl:1
	v_pk_mul_f32 v[66:67], v[60:61], v[52:53] op_sel_hi:[1,0]
	v_mov_b32_dpp v77, v76 row_ror:8 row_mask:0xf bank_mask:0xf bound_ctrl:1
	v_pk_mul_f32 v[68:69], v[76:77], v[56:57] op_sel:[0,1]
	v_pk_mul_f32 v[70:71], v[76:77], v[58:59] op_sel_hi:[1,0]
	v_pk_mul_f32 v[72:73], v[76:77], v[58:59] op_sel:[0,1]
	v_pk_fma_f32 v[66:67], v[76:77], v[56:57], v[66:67] op_sel_hi:[1,0,1]
	v_pk_fma_f32 v[68:69], v[60:61], v[52:53], v[68:69] op_sel:[0,1,0]
	v_pk_fma_f32 v[70:71], v[60:61], v[54:55], v[70:71] op_sel_hi:[1,0,1]
	v_pk_fma_f32 v[72:73], v[60:61], v[54:55], v[72:73] op_sel:[0,1,0]
	v_pk_fma_f32 v[0:1], v[0:1], v[48:49], v[66:67] op_sel_hi:[1,0,1]
	v_pk_fma_f32 v[2:3], v[2:3], v[48:49], v[68:69] op_sel:[0,1,0]
	v_pk_fma_f32 v[4:5], v[4:5], v[50:51], v[70:71] op_sel_hi:[1,0,1]
	v_pk_fma_f32 v[6:7], v[6:7], v[50:51], v[72:73] op_sel:[0,1,0]
	ds_write_b32 v84, v64 offset:1408
	ds_write_b32 v84, v76 offset:13696
	s_waitcnt lgkmcnt(2)
	v_pk_mul_f32 v[8:9], v[0:1], v[12:13] op_sel_hi:[1,0]
	v_pk_mul_f32 v[10:11], v[0:1], v[16:17] op_sel_hi:[1,0]
	ds_read_b128 v[40:43], v80 offset:20736
	v_pk_fma_f32 v[8:9], v[2:3], v[12:13], v[8:9] op_sel:[0,1,0]
	v_pk_fma_f32 v[10:11], v[2:3], v[16:17], v[10:11] op_sel:[0,1,0]
	ds_read_b128 v[44:47], v80 offset:19968
	v_pk_fma_f32 v[8:9], v[4:5], v[14:15], v[8:9] op_sel_hi:[1,0,1]
	v_pk_fma_f32 v[10:11], v[4:5], v[18:19], v[10:11] op_sel_hi:[1,0,1]
	ds_read_b128 v[48:51], v80 offset:20224
	v_pk_fma_f32 v[8:9], v[6:7], v[14:15], v[8:9] op_sel:[0,1,0]
	v_pk_fma_f32 v[10:11], v[6:7], v[18:19], v[10:11] op_sel:[0,1,0]
	ds_read_b128 v[52:55], v80 offset:20480
	v_add_f32_dpp v74, v9, v8 row_ror:8 row_mask:0xf bank_mask:0xf bound_ctrl:1
	v_add_f32_dpp v75, v11, v10 row_ror:8 row_mask:0xf bank_mask:0xf bound_ctrl:1
	ds_read_b128 v[56:59], v80 offset:20992
	v_add_f32_dpp v74, v74, v74 quad_perm:[1,0,3,2] row_mask:0xf bank_mask:0xf bound_ctrl:1
	v_add_f32_dpp v75, v75, v75 quad_perm:[1,0,3,2] row_mask:0xf bank_mask:0xf bound_ctrl:1
	ds_read_b32 v60, v81 offset:21248
	v_add_f32_dpp v74, v74, v74 quad_perm:[2,3,0,1] row_mask:0xf bank_mask:0xf bound_ctrl:1
	v_add_f32_dpp v75, v75, v75 quad_perm:[2,3,0,1] row_mask:0xf bank_mask:0xf bound_ctrl:1
	ds_read_b32 v61, v82 offset:21248
	v_add_f32_dpp v76, v74, v74 row_half_mirror row_mask:0xf bank_mask:0xf bound_ctrl:1
	v_add_f32_dpp v36, v75, v75 row_half_mirror row_mask:0xf bank_mask:0xf bound_ctrl:1
	v_pk_mul_f32 v[66:67], v[32:33], v[24:25] op_sel_hi:[1,0]
	v_mov_b32_dpp v77, v76 row_ror:8 row_mask:0xf bank_mask:0xf bound_ctrl:1
	v_pk_mul_f32 v[68:69], v[76:77], v[28:29] op_sel:[0,1]
	v_pk_mul_f32 v[70:71], v[76:77], v[30:31] op_sel_hi:[1,0]
	v_pk_mul_f32 v[72:73], v[76:77], v[30:31] op_sel:[0,1]
	v_pk_fma_f32 v[66:67], v[76:77], v[28:29], v[66:67] op_sel_hi:[1,0,1]
	v_pk_fma_f32 v[68:69], v[32:33], v[24:25], v[68:69] op_sel:[0,1,0]
	v_pk_fma_f32 v[70:71], v[32:33], v[26:27], v[70:71] op_sel_hi:[1,0,1]
	v_pk_fma_f32 v[72:73], v[32:33], v[26:27], v[72:73] op_sel:[0,1,0]
	v_pk_fma_f32 v[0:1], v[0:1], v[20:21], v[66:67] op_sel_hi:[1,0,1]
	v_pk_fma_f32 v[2:3], v[2:3], v[20:21], v[68:69] op_sel:[0,1,0]
	v_pk_fma_f32 v[4:5], v[4:5], v[22:23], v[70:71] op_sel_hi:[1,0,1]
	v_pk_fma_f32 v[6:7], v[6:7], v[22:23], v[72:73] op_sel:[0,1,0]
	ds_write_b32 v84, v36 offset:1536
	ds_write_b32 v84, v76 offset:13824
	s_waitcnt lgkmcnt(2)
	v_pk_mul_f32 v[8:9], v[0:1], v[40:41] op_sel_hi:[1,0]
	v_pk_mul_f32 v[10:11], v[0:1], v[44:45] op_sel_hi:[1,0]
	ds_read_b128 v[12:15], v80 offset:22272
	v_pk_fma_f32 v[8:9], v[2:3], v[40:41], v[8:9] op_sel:[0,1,0]
	v_pk_fma_f32 v[10:11], v[2:3], v[44:45], v[10:11] op_sel:[0,1,0]
	ds_read_b128 v[16:19], v80 offset:21504
	v_pk_fma_f32 v[8:9], v[4:5], v[42:43], v[8:9] op_sel_hi:[1,0,1]
	v_pk_fma_f32 v[10:11], v[4:5], v[46:47], v[10:11] op_sel_hi:[1,0,1]
	ds_read_b128 v[20:23], v80 offset:21760
	v_pk_fma_f32 v[8:9], v[6:7], v[42:43], v[8:9] op_sel:[0,1,0]
	v_pk_fma_f32 v[10:11], v[6:7], v[46:47], v[10:11] op_sel:[0,1,0]
	ds_read_b128 v[24:27], v80 offset:22016
	v_add_f32_dpp v74, v9, v8 row_ror:8 row_mask:0xf bank_mask:0xf bound_ctrl:1
	v_add_f32_dpp v75, v11, v10 row_ror:8 row_mask:0xf bank_mask:0xf bound_ctrl:1
	ds_read_b128 v[28:31], v80 offset:22528
	v_add_f32_dpp v74, v74, v74 quad_perm:[1,0,3,2] row_mask:0xf bank_mask:0xf bound_ctrl:1
	v_add_f32_dpp v75, v75, v75 quad_perm:[1,0,3,2] row_mask:0xf bank_mask:0xf bound_ctrl:1
	ds_read_b32 v32, v81 offset:22784
	v_add_f32_dpp v74, v74, v74 quad_perm:[2,3,0,1] row_mask:0xf bank_mask:0xf bound_ctrl:1
	v_add_f32_dpp v75, v75, v75 quad_perm:[2,3,0,1] row_mask:0xf bank_mask:0xf bound_ctrl:1
	ds_read_b32 v33, v82 offset:22784
	v_add_f32_dpp v76, v74, v74 row_half_mirror row_mask:0xf bank_mask:0xf bound_ctrl:1
	v_add_f32_dpp v64, v75, v75 row_half_mirror row_mask:0xf bank_mask:0xf bound_ctrl:1
	v_pk_mul_f32 v[66:67], v[60:61], v[52:53] op_sel_hi:[1,0]
	v_mov_b32_dpp v77, v76 row_ror:8 row_mask:0xf bank_mask:0xf bound_ctrl:1
	v_pk_mul_f32 v[68:69], v[76:77], v[56:57] op_sel:[0,1]
	v_pk_mul_f32 v[70:71], v[76:77], v[58:59] op_sel_hi:[1,0]
	v_pk_mul_f32 v[72:73], v[76:77], v[58:59] op_sel:[0,1]
	v_pk_fma_f32 v[66:67], v[76:77], v[56:57], v[66:67] op_sel_hi:[1,0,1]
	v_pk_fma_f32 v[68:69], v[60:61], v[52:53], v[68:69] op_sel:[0,1,0]
	v_pk_fma_f32 v[70:71], v[60:61], v[54:55], v[70:71] op_sel_hi:[1,0,1]
	v_pk_fma_f32 v[72:73], v[60:61], v[54:55], v[72:73] op_sel:[0,1,0]
	v_pk_fma_f32 v[0:1], v[0:1], v[48:49], v[66:67] op_sel_hi:[1,0,1]
	v_pk_fma_f32 v[2:3], v[2:3], v[48:49], v[68:69] op_sel:[0,1,0]
	v_pk_fma_f32 v[4:5], v[4:5], v[50:51], v[70:71] op_sel_hi:[1,0,1]
	v_pk_fma_f32 v[6:7], v[6:7], v[50:51], v[72:73] op_sel:[0,1,0]
	ds_write_b32 v84, v64 offset:1664
	ds_write_b32 v84, v76 offset:13952
	s_waitcnt lgkmcnt(2)
	v_pk_mul_f32 v[8:9], v[0:1], v[12:13] op_sel_hi:[1,0]
	v_pk_mul_f32 v[10:11], v[0:1], v[16:17] op_sel_hi:[1,0]
	ds_read_b128 v[40:43], v80 offset:23808
	v_pk_fma_f32 v[8:9], v[2:3], v[12:13], v[8:9] op_sel:[0,1,0]
	v_pk_fma_f32 v[10:11], v[2:3], v[16:17], v[10:11] op_sel:[0,1,0]
	ds_read_b128 v[44:47], v80 offset:23040
	v_pk_fma_f32 v[8:9], v[4:5], v[14:15], v[8:9] op_sel_hi:[1,0,1]
	v_pk_fma_f32 v[10:11], v[4:5], v[18:19], v[10:11] op_sel_hi:[1,0,1]
	ds_read_b128 v[48:51], v80 offset:23296
	v_pk_fma_f32 v[8:9], v[6:7], v[14:15], v[8:9] op_sel:[0,1,0]
	v_pk_fma_f32 v[10:11], v[6:7], v[18:19], v[10:11] op_sel:[0,1,0]
	ds_read_b128 v[52:55], v80 offset:23552
	v_add_f32_dpp v74, v9, v8 row_ror:8 row_mask:0xf bank_mask:0xf bound_ctrl:1
	v_add_f32_dpp v75, v11, v10 row_ror:8 row_mask:0xf bank_mask:0xf bound_ctrl:1
	ds_read_b128 v[56:59], v80 offset:24064
	v_add_f32_dpp v74, v74, v74 quad_perm:[1,0,3,2] row_mask:0xf bank_mask:0xf bound_ctrl:1
	v_add_f32_dpp v75, v75, v75 quad_perm:[1,0,3,2] row_mask:0xf bank_mask:0xf bound_ctrl:1
	ds_read_b32 v60, v81 offset:24320
	v_add_f32_dpp v74, v74, v74 quad_perm:[2,3,0,1] row_mask:0xf bank_mask:0xf bound_ctrl:1
	v_add_f32_dpp v75, v75, v75 quad_perm:[2,3,0,1] row_mask:0xf bank_mask:0xf bound_ctrl:1
	ds_read_b32 v61, v82 offset:24320
	v_add_f32_dpp v76, v74, v74 row_half_mirror row_mask:0xf bank_mask:0xf bound_ctrl:1
	v_add_f32_dpp v36, v75, v75 row_half_mirror row_mask:0xf bank_mask:0xf bound_ctrl:1
	v_pk_mul_f32 v[66:67], v[32:33], v[24:25] op_sel_hi:[1,0]
	v_mov_b32_dpp v77, v76 row_ror:8 row_mask:0xf bank_mask:0xf bound_ctrl:1
	v_pk_mul_f32 v[68:69], v[76:77], v[28:29] op_sel:[0,1]
	v_pk_mul_f32 v[70:71], v[76:77], v[30:31] op_sel_hi:[1,0]
	v_pk_mul_f32 v[72:73], v[76:77], v[30:31] op_sel:[0,1]
	v_pk_fma_f32 v[66:67], v[76:77], v[28:29], v[66:67] op_sel_hi:[1,0,1]
	v_pk_fma_f32 v[68:69], v[32:33], v[24:25], v[68:69] op_sel:[0,1,0]
	v_pk_fma_f32 v[70:71], v[32:33], v[26:27], v[70:71] op_sel_hi:[1,0,1]
	v_pk_fma_f32 v[72:73], v[32:33], v[26:27], v[72:73] op_sel:[0,1,0]
	v_pk_fma_f32 v[0:1], v[0:1], v[20:21], v[66:67] op_sel_hi:[1,0,1]
	v_pk_fma_f32 v[2:3], v[2:3], v[20:21], v[68:69] op_sel:[0,1,0]
	v_pk_fma_f32 v[4:5], v[4:5], v[22:23], v[70:71] op_sel_hi:[1,0,1]
	v_pk_fma_f32 v[6:7], v[6:7], v[22:23], v[72:73] op_sel:[0,1,0]
	ds_write_b32 v84, v36 offset:1792
	ds_write_b32 v84, v76 offset:14080
	s_waitcnt lgkmcnt(2)
	v_pk_mul_f32 v[8:9], v[0:1], v[40:41] op_sel_hi:[1,0]
	v_pk_mul_f32 v[10:11], v[0:1], v[44:45] op_sel_hi:[1,0]
	ds_read_b128 v[12:15], v80 offset:25344
	v_pk_fma_f32 v[8:9], v[2:3], v[40:41], v[8:9] op_sel:[0,1,0]
	v_pk_fma_f32 v[10:11], v[2:3], v[44:45], v[10:11] op_sel:[0,1,0]
	ds_read_b128 v[16:19], v80 offset:24576
	v_pk_fma_f32 v[8:9], v[4:5], v[42:43], v[8:9] op_sel_hi:[1,0,1]
	v_pk_fma_f32 v[10:11], v[4:5], v[46:47], v[10:11] op_sel_hi:[1,0,1]
	ds_read_b128 v[20:23], v80 offset:24832
	v_pk_fma_f32 v[8:9], v[6:7], v[42:43], v[8:9] op_sel:[0,1,0]
	v_pk_fma_f32 v[10:11], v[6:7], v[46:47], v[10:11] op_sel:[0,1,0]
	ds_read_b128 v[24:27], v80 offset:25088
	v_add_f32_dpp v74, v9, v8 row_ror:8 row_mask:0xf bank_mask:0xf bound_ctrl:1
	v_add_f32_dpp v75, v11, v10 row_ror:8 row_mask:0xf bank_mask:0xf bound_ctrl:1
	ds_read_b128 v[28:31], v80 offset:25600
	v_add_f32_dpp v74, v74, v74 quad_perm:[1,0,3,2] row_mask:0xf bank_mask:0xf bound_ctrl:1
	v_add_f32_dpp v75, v75, v75 quad_perm:[1,0,3,2] row_mask:0xf bank_mask:0xf bound_ctrl:1
	ds_read_b32 v32, v81 offset:25856
	v_add_f32_dpp v74, v74, v74 quad_perm:[2,3,0,1] row_mask:0xf bank_mask:0xf bound_ctrl:1
	v_add_f32_dpp v75, v75, v75 quad_perm:[2,3,0,1] row_mask:0xf bank_mask:0xf bound_ctrl:1
	ds_read_b32 v33, v82 offset:25856
	v_add_f32_dpp v76, v74, v74 row_half_mirror row_mask:0xf bank_mask:0xf bound_ctrl:1
	v_add_f32_dpp v64, v75, v75 row_half_mirror row_mask:0xf bank_mask:0xf bound_ctrl:1
	v_pk_mul_f32 v[66:67], v[60:61], v[52:53] op_sel_hi:[1,0]
	v_mov_b32_dpp v77, v76 row_ror:8 row_mask:0xf bank_mask:0xf bound_ctrl:1
	v_pk_mul_f32 v[68:69], v[76:77], v[56:57] op_sel:[0,1]
	v_pk_mul_f32 v[70:71], v[76:77], v[58:59] op_sel_hi:[1,0]
	v_pk_mul_f32 v[72:73], v[76:77], v[58:59] op_sel:[0,1]
	v_pk_fma_f32 v[66:67], v[76:77], v[56:57], v[66:67] op_sel_hi:[1,0,1]
	v_pk_fma_f32 v[68:69], v[60:61], v[52:53], v[68:69] op_sel:[0,1,0]
	v_pk_fma_f32 v[70:71], v[60:61], v[54:55], v[70:71] op_sel_hi:[1,0,1]
	v_pk_fma_f32 v[72:73], v[60:61], v[54:55], v[72:73] op_sel:[0,1,0]
	v_pk_fma_f32 v[0:1], v[0:1], v[48:49], v[66:67] op_sel_hi:[1,0,1]
	v_pk_fma_f32 v[2:3], v[2:3], v[48:49], v[68:69] op_sel:[0,1,0]
	v_pk_fma_f32 v[4:5], v[4:5], v[50:51], v[70:71] op_sel_hi:[1,0,1]
	v_pk_fma_f32 v[6:7], v[6:7], v[50:51], v[72:73] op_sel:[0,1,0]
	ds_write_b32 v84, v64 offset:1920
	ds_write_b32 v84, v76 offset:14208
	s_cmp_eq_u32 s4, 64
	s_cbranch_scc1 .Lrec_chunk_end
	s_waitcnt lgkmcnt(2)
	v_pk_mul_f32 v[8:9], v[0:1], v[12:13] op_sel_hi:[1,0]
	v_pk_mul_f32 v[10:11], v[0:1], v[16:17] op_sel_hi:[1,0]
	ds_read_b128 v[40:43], v80 offset:26880
	v_pk_fma_f32 v[8:9], v[2:3], v[12:13], v[8:9] op_sel:[0,1,0]
	v_pk_fma_f32 v[10:11], v[2:3], v[16:17], v[10:11] op_sel:[0,1,0]
	ds_read_b128 v[44:47], v80 offset:26112
	v_pk_fma_f32 v[8:9], v[4:5], v[14:15], v[8:9] op_sel_hi:[1,0,1]
	v_pk_fma_f32 v[10:11], v[4:5], v[18:19], v[10:11] op_sel_hi:[1,0,1]
	ds_read_b128 v[48:51], v80 offset:26368
	v_pk_fma_f32 v[8:9], v[6:7], v[14:15], v[8:9] op_sel:[0,1,0]
	v_pk_fma_f32 v[10:11], v[6:7], v[18:19], v[10:11] op_sel:[0,1,0]
	ds_read_b128 v[52:55], v80 offset:26624
	v_add_f32_dpp v74, v9, v8 row_ror:8 row_mask:0xf bank_mask:0xf bound_ctrl:1
	v_add_f32_dpp v75, v11, v10 row_ror:8 row_mask:0xf bank_mask:0xf bound_ctrl:1
	ds_read_b128 v[56:59], v80 offset:27136
	v_add_f32_dpp v74, v74, v74 quad_perm:[1,0,3,2] row_mask:0xf bank_mask:0xf bound_ctrl:1
	v_add_f32_dpp v75, v75, v75 quad_perm:[1,0,3,2] row_mask:0xf bank_mask:0xf bound_ctrl:1
	ds_read_b32 v60, v81 offset:27392
	v_add_f32_dpp v74, v74, v74 quad_perm:[2,3,0,1] row_mask:0xf bank_mask:0xf bound_ctrl:1
	v_add_f32_dpp v75, v75, v75 quad_perm:[2,3,0,1] row_mask:0xf bank_mask:0xf bound_ctrl:1
	ds_read_b32 v61, v82 offset:27392
	v_add_f32_dpp v76, v74, v74 row_half_mirror row_mask:0xf bank_mask:0xf bound_ctrl:1
	v_add_f32_dpp v36, v75, v75 row_half_mirror row_mask:0xf bank_mask:0xf bound_ctrl:1
	v_pk_mul_f32 v[66:67], v[32:33], v[24:25] op_sel_hi:[1,0]
	v_mov_b32_dpp v77, v76 row_ror:8 row_mask:0xf bank_mask:0xf bound_ctrl:1
	v_pk_mul_f32 v[68:69], v[76:77], v[28:29] op_sel:[0,1]
	v_pk_mul_f32 v[70:71], v[76:77], v[30:31] op_sel_hi:[1,0]
	v_pk_mul_f32 v[72:73], v[76:77], v[30:31] op_sel:[0,1]
	v_pk_fma_f32 v[66:67], v[76:77], v[28:29], v[66:67] op_sel_hi:[1,0,1]
	v_pk_fma_f32 v[68:69], v[32:33], v[24:25], v[68:69] op_sel:[0,1,0]
	v_pk_fma_f32 v[70:71], v[32:33], v[26:27], v[70:71] op_sel_hi:[1,0,1]
	v_pk_fma_f32 v[72:73], v[32:33], v[26:27], v[72:73] op_sel:[0,1,0]
	v_pk_fma_f32 v[0:1], v[0:1], v[20:21], v[66:67] op_sel_hi:[1,0,1]
	v_pk_fma_f32 v[2:3], v[2:3], v[20:21], v[68:69] op_sel:[0,1,0]
	v_pk_fma_f32 v[4:5], v[4:5], v[22:23], v[70:71] op_sel_hi:[1,0,1]
	v_pk_fma_f32 v[6:7], v[6:7], v[22:23], v[72:73] op_sel:[0,1,0]
	ds_write_b32 v84, v36 offset:2048
	ds_write_b32 v84, v76 offset:14336
	s_waitcnt lgkmcnt(2)
	v_pk_mul_f32 v[8:9], v[0:1], v[40:41] op_sel_hi:[1,0]
	v_pk_mul_f32 v[10:11], v[0:1], v[44:45] op_sel_hi:[1,0]
	ds_read_b128 v[12:15], v80 offset:28416
	v_pk_fma_f32 v[8:9], v[2:3], v[40:41], v[8:9] op_sel:[0,1,0]
	v_pk_fma_f32 v[10:11], v[2:3], v[44:45], v[10:11] op_sel:[0,1,0]
	ds_read_b128 v[16:19], v80 offset:27648
	v_pk_fma_f32 v[8:9], v[4:5], v[42:43], v[8:9] op_sel_hi:[1,0,1]
	v_pk_fma_f32 v[10:11], v[4:5], v[46:47], v[10:11] op_sel_hi:[1,0,1]
	ds_read_b128 v[20:23], v80 offset:27904
	v_pk_fma_f32 v[8:9], v[6:7], v[42:43], v[8:9] op_sel:[0,1,0]
	v_pk_fma_f32 v[10:11], v[6:7], v[46:47], v[10:11] op_sel:[0,1,0]
	ds_read_b128 v[24:27], v80 offset:28160
	v_add_f32_dpp v74, v9, v8 row_ror:8 row_mask:0xf bank_mask:0xf bound_ctrl:1
	v_add_f32_dpp v75, v11, v10 row_ror:8 row_mask:0xf bank_mask:0xf bound_ctrl:1
	ds_read_b128 v[28:31], v80 offset:28672
	v_add_f32_dpp v74, v74, v74 quad_perm:[1,0,3,2] row_mask:0xf bank_mask:0xf bound_ctrl:1
	v_add_f32_dpp v75, v75, v75 quad_perm:[1,0,3,2] row_mask:0xf bank_mask:0xf bound_ctrl:1
	ds_read_b32 v32, v81 offset:28928
	v_add_f32_dpp v74, v74, v74 quad_perm:[2,3,0,1] row_mask:0xf bank_mask:0xf bound_ctrl:1
	v_add_f32_dpp v75, v75, v75 quad_perm:[2,3,0,1] row_mask:0xf bank_mask:0xf bound_ctrl:1
	ds_read_b32 v33, v82 offset:28928
	v_add_f32_dpp v76, v74, v74 row_half_mirror row_mask:0xf bank_mask:0xf bound_ctrl:1
	v_add_f32_dpp v64, v75, v75 row_half_mirror row_mask:0xf bank_mask:0xf bound_ctrl:1
	v_pk_mul_f32 v[66:67], v[60:61], v[52:53] op_sel_hi:[1,0]
	v_mov_b32_dpp v77, v76 row_ror:8 row_mask:0xf bank_mask:0xf bound_ctrl:1
	v_pk_mul_f32 v[68:69], v[76:77], v[56:57] op_sel:[0,1]
	v_pk_mul_f32 v[70:71], v[76:77], v[58:59] op_sel_hi:[1,0]
	v_pk_mul_f32 v[72:73], v[76:77], v[58:59] op_sel:[0,1]
	v_pk_fma_f32 v[66:67], v[76:77], v[56:57], v[66:67] op_sel_hi:[1,0,1]
	v_pk_fma_f32 v[68:69], v[60:61], v[52:53], v[68:69] op_sel:[0,1,0]
	v_pk_fma_f32 v[70:71], v[60:61], v[54:55], v[70:71] op_sel_hi:[1,0,1]
	v_pk_fma_f32 v[72:73], v[60:61], v[54:55], v[72:73] op_sel:[0,1,0]
	v_pk_fma_f32 v[0:1], v[0:1], v[48:49], v[66:67] op_sel_hi:[1,0,1]
	v_pk_fma_f32 v[2:3], v[2:3], v[48:49], v[68:69] op_sel:[0,1,0]
	v_pk_fma_f32 v[4:5], v[4:5], v[50:51], v[70:71] op_sel_hi:[1,0,1]
	v_pk_fma_f32 v[6:7], v[6:7], v[50:51], v[72:73] op_sel:[0,1,0]
	ds_write_b32 v84, v64 offset:2176
	ds_write_b32 v84, v76 offset:14464
	s_waitcnt lgkmcnt(2)
	v_pk_mul_f32 v[8:9], v[0:1], v[12:13] op_sel_hi:[1,0]
	v_pk_mul_f32 v[10:11], v[0:1], v[16:17] op_sel_hi:[1,0]
	ds_read_b128 v[40:43], v80 offset:29952
	v_pk_fma_f32 v[8:9], v[2:3], v[12:13], v[8:9] op_sel:[0,1,0]
	v_pk_fma_f32 v[10:11], v[2:3], v[16:17], v[10:11] op_sel:[0,1,0]
	ds_read_b128 v[44:47], v80 offset:29184
	v_pk_fma_f32 v[8:9], v[4:5], v[14:15], v[8:9] op_sel_hi:[1,0,1]
	v_pk_fma_f32 v[10:11], v[4:5], v[18:19], v[10:11] op_sel_hi:[1,0,1]
	ds_read_b128 v[48:51], v80 offset:29440
	v_pk_fma_f32 v[8:9], v[6:7], v[14:15], v[8:9] op_sel:[0,1,0]
	v_pk_fma_f32 v[10:11], v[6:7], v[18:19], v[10:11] op_sel:[0,1,0]
	ds_read_b128 v[52:55], v80 offset:29696
	v_add_f32_dpp v74, v9, v8 row_ror:8 row_mask:0xf bank_mask:0xf bound_ctrl:1
	v_add_f32_dpp v75, v11, v10 row_ror:8 row_mask:0xf bank_mask:0xf bound_ctrl:1
	ds_read_b128 v[56:59], v80 offset:30208
	v_add_f32_dpp v74, v74, v74 quad_perm:[1,0,3,2] row_mask:0xf bank_mask:0xf bound_ctrl:1
	v_add_f32_dpp v75, v75, v75 quad_perm:[1,0,3,2] row_mask:0xf bank_mask:0xf bound_ctrl:1
	ds_read_b32 v60, v81 offset:30464
	v_add_f32_dpp v74, v74, v74 quad_perm:[2,3,0,1] row_mask:0xf bank_mask:0xf bound_ctrl:1
	v_add_f32_dpp v75, v75, v75 quad_perm:[2,3,0,1] row_mask:0xf bank_mask:0xf bound_ctrl:1
	ds_read_b32 v61, v82 offset:30464
	v_add_f32_dpp v76, v74, v74 row_half_mirror row_mask:0xf bank_mask:0xf bound_ctrl:1
	v_add_f32_dpp v36, v75, v75 row_half_mirror row_mask:0xf bank_mask:0xf bound_ctrl:1
	v_pk_mul_f32 v[66:67], v[32:33], v[24:25] op_sel_hi:[1,0]
	v_mov_b32_dpp v77, v76 row_ror:8 row_mask:0xf bank_mask:0xf bound_ctrl:1
	v_pk_mul_f32 v[68:69], v[76:77], v[28:29] op_sel:[0,1]
	v_pk_mul_f32 v[70:71], v[76:77], v[30:31] op_sel_hi:[1,0]
	v_pk_mul_f32 v[72:73], v[76:77], v[30:31] op_sel:[0,1]
	v_pk_fma_f32 v[66:67], v[76:77], v[28:29], v[66:67] op_sel_hi:[1,0,1]
	v_pk_fma_f32 v[68:69], v[32:33], v[24:25], v[68:69] op_sel:[0,1,0]
	v_pk_fma_f32 v[70:71], v[32:33], v[26:27], v[70:71] op_sel_hi:[1,0,1]
	v_pk_fma_f32 v[72:73], v[32:33], v[26:27], v[72:73] op_sel:[0,1,0]
	v_pk_fma_f32 v[0:1], v[0:1], v[20:21], v[66:67] op_sel_hi:[1,0,1]
	v_pk_fma_f32 v[2:3], v[2:3], v[20:21], v[68:69] op_sel:[0,1,0]
	v_pk_fma_f32 v[4:5], v[4:5], v[22:23], v[70:71] op_sel_hi:[1,0,1]
	v_pk_fma_f32 v[6:7], v[6:7], v[22:23], v[72:73] op_sel:[0,1,0]
	ds_write_b32 v84, v36 offset:2304
	ds_write_b32 v84, v76 offset:14592
	s_waitcnt lgkmcnt(2)
	v_pk_mul_f32 v[8:9], v[0:1], v[40:41] op_sel_hi:[1,0]
	v_pk_mul_f32 v[10:11], v[0:1], v[44:45] op_sel_hi:[1,0]
	ds_read_b128 v[12:15], v80 offset:31488
	v_pk_fma_f32 v[8:9], v[2:3], v[40:41], v[8:9] op_sel:[0,1,0]
	v_pk_fma_f32 v[10:11], v[2:3], v[44:45], v[10:11] op_sel:[0,1,0]
	ds_read_b128 v[16:19], v80 offset:30720
	v_pk_fma_f32 v[8:9], v[4:5], v[42:43], v[8:9] op_sel_hi:[1,0,1]
	v_pk_fma_f32 v[10:11], v[4:5], v[46:47], v[10:11] op_sel_hi:[1,0,1]
	ds_read_b128 v[20:23], v80 offset:30976
	v_pk_fma_f32 v[8:9], v[6:7], v[42:43], v[8:9] op_sel:[0,1,0]
	v_pk_fma_f32 v[10:11], v[6:7], v[46:47], v[10:11] op_sel:[0,1,0]
	ds_read_b128 v[24:27], v80 offset:31232
	v_add_f32_dpp v74, v9, v8 row_ror:8 row_mask:0xf bank_mask:0xf bound_ctrl:1
	v_add_f32_dpp v75, v11, v10 row_ror:8 row_mask:0xf bank_mask:0xf bound_ctrl:1
	ds_read_b128 v[28:31], v80 offset:31744
	v_add_f32_dpp v74, v74, v74 quad_perm:[1,0,3,2] row_mask:0xf bank_mask:0xf bound_ctrl:1
	v_add_f32_dpp v75, v75, v75 quad_perm:[1,0,3,2] row_mask:0xf bank_mask:0xf bound_ctrl:1
	ds_read_b32 v32, v81 offset:32000
	v_add_f32_dpp v74, v74, v74 quad_perm:[2,3,0,1] row_mask:0xf bank_mask:0xf bound_ctrl:1
	v_add_f32_dpp v75, v75, v75 quad_perm:[2,3,0,1] row_mask:0xf bank_mask:0xf bound_ctrl:1
	ds_read_b32 v33, v82 offset:32000
	v_add_f32_dpp v76, v74, v74 row_half_mirror row_mask:0xf bank_mask:0xf bound_ctrl:1
	v_add_f32_dpp v64, v75, v75 row_half_mirror row_mask:0xf bank_mask:0xf bound_ctrl:1
	v_pk_mul_f32 v[66:67], v[60:61], v[52:53] op_sel_hi:[1,0]
	v_mov_b32_dpp v77, v76 row_ror:8 row_mask:0xf bank_mask:0xf bound_ctrl:1
	v_pk_mul_f32 v[68:69], v[76:77], v[56:57] op_sel:[0,1]
	v_pk_mul_f32 v[70:71], v[76:77], v[58:59] op_sel_hi:[1,0]
	v_pk_mul_f32 v[72:73], v[76:77], v[58:59] op_sel:[0,1]
	v_pk_fma_f32 v[66:67], v[76:77], v[56:57], v[66:67] op_sel_hi:[1,0,1]
	v_pk_fma_f32 v[68:69], v[60:61], v[52:53], v[68:69] op_sel:[0,1,0]
	v_pk_fma_f32 v[70:71], v[60:61], v[54:55], v[70:71] op_sel_hi:[1,0,1]
	v_pk_fma_f32 v[72:73], v[60:61], v[54:55], v[72:73] op_sel:[0,1,0]
	v_pk_fma_f32 v[0:1], v[0:1], v[48:49], v[66:67] op_sel_hi:[1,0,1]
	v_pk_fma_f32 v[2:3], v[2:3], v[48:49], v[68:69] op_sel:[0,1,0]
	v_pk_fma_f32 v[4:5], v[4:5], v[50:51], v[70:71] op_sel_hi:[1,0,1]
	v_pk_fma_f32 v[6:7], v[6:7], v[50:51], v[72:73] op_sel:[0,1,0]
	ds_write_b32 v84, v64 offset:2432
	ds_write_b32 v84, v76 offset:14720
	s_waitcnt lgkmcnt(2)
	v_pk_mul_f32 v[8:9], v[0:1], v[12:13] op_sel_hi:[1,0]
	v_pk_mul_f32 v[10:11], v[0:1], v[16:17] op_sel_hi:[1,0]
	ds_read_b128 v[40:43], v80 offset:33024
	v_pk_fma_f32 v[8:9], v[2:3], v[12:13], v[8:9] op_sel:[0,1,0]
	v_pk_fma_f32 v[10:11], v[2:3], v[16:17], v[10:11] op_sel:[0,1,0]
	ds_read_b128 v[44:47], v80 offset:32256
	v_pk_fma_f32 v[8:9], v[4:5], v[14:15], v[8:9] op_sel_hi:[1,0,1]
	v_pk_fma_f32 v[10:11], v[4:5], v[18:19], v[10:11] op_sel_hi:[1,0,1]
	ds_read_b128 v[48:51], v80 offset:32512
	v_pk_fma_f32 v[8:9], v[6:7], v[14:15], v[8:9] op_sel:[0,1,0]
	v_pk_fma_f32 v[10:11], v[6:7], v[18:19], v[10:11] op_sel:[0,1,0]
	ds_read_b128 v[52:55], v80 offset:32768
	v_add_f32_dpp v74, v9, v8 row_ror:8 row_mask:0xf bank_mask:0xf bound_ctrl:1
	v_add_f32_dpp v75, v11, v10 row_ror:8 row_mask:0xf bank_mask:0xf bound_ctrl:1
	ds_read_b128 v[56:59], v80 offset:33280
	v_add_f32_dpp v74, v74, v74 quad_perm:[1,0,3,2] row_mask:0xf bank_mask:0xf bound_ctrl:1
	v_add_f32_dpp v75, v75, v75 quad_perm:[1,0,3,2] row_mask:0xf bank_mask:0xf bound_ctrl:1
	ds_read_b32 v60, v81 offset:33536
	v_add_f32_dpp v74, v74, v74 quad_perm:[2,3,0,1] row_mask:0xf bank_mask:0xf bound_ctrl:1
	v_add_f32_dpp v75, v75, v75 quad_perm:[2,3,0,1] row_mask:0xf bank_mask:0xf bound_ctrl:1
	ds_read_b32 v61, v82 offset:33536
	v_add_f32_dpp v76, v74, v74 row_half_mirror row_mask:0xf bank_mask:0xf bound_ctrl:1
	v_add_f32_dpp v36, v75, v75 row_half_mirror row_mask:0xf bank_mask:0xf bound_ctrl:1
	v_pk_mul_f32 v[66:67], v[32:33], v[24:25] op_sel_hi:[1,0]
	v_mov_b32_dpp v77, v76 row_ror:8 row_mask:0xf bank_mask:0xf bound_ctrl:1
	v_pk_mul_f32 v[68:69], v[76:77], v[28:29] op_sel:[0,1]
	v_pk_mul_f32 v[70:71], v[76:77], v[30:31] op_sel_hi:[1,0]
	v_pk_mul_f32 v[72:73], v[76:77], v[30:31] op_sel:[0,1]
	v_pk_fma_f32 v[66:67], v[76:77], v[28:29], v[66:67] op_sel_hi:[1,0,1]
	v_pk_fma_f32 v[68:69], v[32:33], v[24:25], v[68:69] op_sel:[0,1,0]
	v_pk_fma_f32 v[70:71], v[32:33], v[26:27], v[70:71] op_sel_hi:[1,0,1]
	v_pk_fma_f32 v[72:73], v[32:33], v[26:27], v[72:73] op_sel:[0,1,0]
	v_pk_fma_f32 v[0:1], v[0:1], v[20:21], v[66:67] op_sel_hi:[1,0,1]
	v_pk_fma_f32 v[2:3], v[2:3], v[20:21], v[68:69] op_sel:[0,1,0]
	v_pk_fma_f32 v[4:5], v[4:5], v[22:23], v[70:71] op_sel_hi:[1,0,1]
	v_pk_fma_f32 v[6:7], v[6:7], v[22:23], v[72:73] op_sel:[0,1,0]
	ds_write_b32 v84, v36 offset:2560
	ds_write_b32 v84, v76 offset:14848
	s_waitcnt lgkmcnt(2)
	v_pk_mul_f32 v[8:9], v[0:1], v[40:41] op_sel_hi:[1,0]
	v_pk_mul_f32 v[10:11], v[0:1], v[44:45] op_sel_hi:[1,0]
	ds_read_b128 v[12:15], v80 offset:34560
	v_pk_fma_f32 v[8:9], v[2:3], v[40:41], v[8:9] op_sel:[0,1,0]
	v_pk_fma_f32 v[10:11], v[2:3], v[44:45], v[10:11] op_sel:[0,1,0]
	ds_read_b128 v[16:19], v80 offset:33792
	v_pk_fma_f32 v[8:9], v[4:5], v[42:43], v[8:9] op_sel_hi:[1,0,1]
	v_pk_fma_f32 v[10:11], v[4:5], v[46:47], v[10:11] op_sel_hi:[1,0,1]
	ds_read_b128 v[20:23], v80 offset:34048
	v_pk_fma_f32 v[8:9], v[6:7], v[42:43], v[8:9] op_sel:[0,1,0]
	v_pk_fma_f32 v[10:11], v[6:7], v[46:47], v[10:11] op_sel:[0,1,0]
	ds_read_b128 v[24:27], v80 offset:34304
	v_add_f32_dpp v74, v9, v8 row_ror:8 row_mask:0xf bank_mask:0xf bound_ctrl:1
	v_add_f32_dpp v75, v11, v10 row_ror:8 row_mask:0xf bank_mask:0xf bound_ctrl:1
	ds_read_b128 v[28:31], v80 offset:34816
	v_add_f32_dpp v74, v74, v74 quad_perm:[1,0,3,2] row_mask:0xf bank_mask:0xf bound_ctrl:1
	v_add_f32_dpp v75, v75, v75 quad_perm:[1,0,3,2] row_mask:0xf bank_mask:0xf bound_ctrl:1
	ds_read_b32 v32, v81 offset:35072
	v_add_f32_dpp v74, v74, v74 quad_perm:[2,3,0,1] row_mask:0xf bank_mask:0xf bound_ctrl:1
	v_add_f32_dpp v75, v75, v75 quad_perm:[2,3,0,1] row_mask:0xf bank_mask:0xf bound_ctrl:1
	ds_read_b32 v33, v82 offset:35072
	v_add_f32_dpp v76, v74, v74 row_half_mirror row_mask:0xf bank_mask:0xf bound_ctrl:1
	v_add_f32_dpp v64, v75, v75 row_half_mirror row_mask:0xf bank_mask:0xf bound_ctrl:1
	v_pk_mul_f32 v[66:67], v[60:61], v[52:53] op_sel_hi:[1,0]
	v_mov_b32_dpp v77, v76 row_ror:8 row_mask:0xf bank_mask:0xf bound_ctrl:1
	v_pk_mul_f32 v[68:69], v[76:77], v[56:57] op_sel:[0,1]
	v_pk_mul_f32 v[70:71], v[76:77], v[58:59] op_sel_hi:[1,0]
	v_pk_mul_f32 v[72:73], v[76:77], v[58:59] op_sel:[0,1]
	v_pk_fma_f32 v[66:67], v[76:77], v[56:57], v[66:67] op_sel_hi:[1,0,1]
	v_pk_fma_f32 v[68:69], v[60:61], v[52:53], v[68:69] op_sel:[0,1,0]
	v_pk_fma_f32 v[70:71], v[60:61], v[54:55], v[70:71] op_sel_hi:[1,0,1]
	v_pk_fma_f32 v[72:73], v[60:61], v[54:55], v[72:73] op_sel:[0,1,0]
	v_pk_fma_f32 v[0:1], v[0:1], v[48:49], v[66:67] op_sel_hi:[1,0,1]
	v_pk_fma_f32 v[2:3], v[2:3], v[48:49], v[68:69] op_sel:[0,1,0]
	v_pk_fma_f32 v[4:5], v[4:5], v[50:51], v[70:71] op_sel_hi:[1,0,1]
	v_pk_fma_f32 v[6:7], v[6:7], v[50:51], v[72:73] op_sel:[0,1,0]
	ds_write_b32 v84, v64 offset:2688
	ds_write_b32 v84, v76 offset:14976
	s_waitcnt lgkmcnt(2)
	v_pk_mul_f32 v[8:9], v[0:1], v[12:13] op_sel_hi:[1,0]
	v_pk_mul_f32 v[10:11], v[0:1], v[16:17] op_sel_hi:[1,0]
	ds_read_b128 v[40:43], v80 offset:36096
	v_pk_fma_f32 v[8:9], v[2:3], v[12:13], v[8:9] op_sel:[0,1,0]
	v_pk_fma_f32 v[10:11], v[2:3], v[16:17], v[10:11] op_sel:[0,1,0]
	ds_read_b128 v[44:47], v80 offset:35328
	v_pk_fma_f32 v[8:9], v[4:5], v[14:15], v[8:9] op_sel_hi:[1,0,1]
	v_pk_fma_f32 v[10:11], v[4:5], v[18:19], v[10:11] op_sel_hi:[1,0,1]
	ds_read_b128 v[48:51], v80 offset:35584
	v_pk_fma_f32 v[8:9], v[6:7], v[14:15], v[8:9] op_sel:[0,1,0]
	v_pk_fma_f32 v[10:11], v[6:7], v[18:19], v[10:11] op_sel:[0,1,0]
	ds_read_b128 v[52:55], v80 offset:35840
	v_add_f32_dpp v74, v9, v8 row_ror:8 row_mask:0xf bank_mask:0xf bound_ctrl:1
	v_add_f32_dpp v75, v11, v10 row_ror:8 row_mask:0xf bank_mask:0xf bound_ctrl:1
	ds_read_b128 v[56:59], v80 offset:36352
	v_add_f32_dpp v74, v74, v74 quad_perm:[1,0,3,2] row_mask:0xf bank_mask:0xf bound_ctrl:1
	v_add_f32_dpp v75, v75, v75 quad_perm:[1,0,3,2] row_mask:0xf bank_mask:0xf bound_ctrl:1
	ds_read_b32 v60, v81 offset:36608
	v_add_f32_dpp v74, v74, v74 quad_perm:[2,3,0,1] row_mask:0xf bank_mask:0xf bound_ctrl:1
	v_add_f32_dpp v75, v75, v75 quad_perm:[2,3,0,1] row_mask:0xf bank_mask:0xf bound_ctrl:1
	ds_read_b32 v61, v82 offset:36608
	v_add_f32_dpp v76, v74, v74 row_half_mirror row_mask:0xf bank_mask:0xf bound_ctrl:1
	v_add_f32_dpp v36, v75, v75 row_half_mirror row_mask:0xf bank_mask:0xf bound_ctrl:1
	v_pk_mul_f32 v[66:67], v[32:33], v[24:25] op_sel_hi:[1,0]
	v_mov_b32_dpp v77, v76 row_ror:8 row_mask:0xf bank_mask:0xf bound_ctrl:1
	v_pk_mul_f32 v[68:69], v[76:77], v[28:29] op_sel:[0,1]
	v_pk_mul_f32 v[70:71], v[76:77], v[30:31] op_sel_hi:[1,0]
	v_pk_mul_f32 v[72:73], v[76:77], v[30:31] op_sel:[0,1]
	v_pk_fma_f32 v[66:67], v[76:77], v[28:29], v[66:67] op_sel_hi:[1,0,1]
	v_pk_fma_f32 v[68:69], v[32:33], v[24:25], v[68:69] op_sel:[0,1,0]
	v_pk_fma_f32 v[70:71], v[32:33], v[26:27], v[70:71] op_sel_hi:[1,0,1]
	v_pk_fma_f32 v[72:73], v[32:33], v[26:27], v[72:73] op_sel:[0,1,0]
	v_pk_fma_f32 v[0:1], v[0:1], v[20:21], v[66:67] op_sel_hi:[1,0,1]
	v_pk_fma_f32 v[2:3], v[2:3], v[20:21], v[68:69] op_sel:[0,1,0]
	v_pk_fma_f32 v[4:5], v[4:5], v[22:23], v[70:71] op_sel_hi:[1,0,1]
	v_pk_fma_f32 v[6:7], v[6:7], v[22:23], v[72:73] op_sel:[0,1,0]
	ds_write_b32 v84, v36 offset:2816
	ds_write_b32 v84, v76 offset:15104
	s_waitcnt lgkmcnt(2)
	v_pk_mul_f32 v[8:9], v[0:1], v[40:41] op_sel_hi:[1,0]
	v_pk_mul_f32 v[10:11], v[0:1], v[44:45] op_sel_hi:[1,0]
	ds_read_b128 v[12:15], v80 offset:37632
	v_pk_fma_f32 v[8:9], v[2:3], v[40:41], v[8:9] op_sel:[0,1,0]
	v_pk_fma_f32 v[10:11], v[2:3], v[44:45], v[10:11] op_sel:[0,1,0]
	ds_read_b128 v[16:19], v80 offset:36864
	v_pk_fma_f32 v[8:9], v[4:5], v[42:43], v[8:9] op_sel_hi:[1,0,1]
	v_pk_fma_f32 v[10:11], v[4:5], v[46:47], v[10:11] op_sel_hi:[1,0,1]
	ds_read_b128 v[20:23], v80 offset:37120
	v_pk_fma_f32 v[8:9], v[6:7], v[42:43], v[8:9] op_sel:[0,1,0]
	v_pk_fma_f32 v[10:11], v[6:7], v[46:47], v[10:11] op_sel:[0,1,0]
	ds_read_b128 v[24:27], v80 offset:37376
	v_add_f32_dpp v74, v9, v8 row_ror:8 row_mask:0xf bank_mask:0xf bound_ctrl:1
	v_add_f32_dpp v75, v11, v10 row_ror:8 row_mask:0xf bank_mask:0xf bound_ctrl:1
	ds_read_b128 v[28:31], v80 offset:37888
	v_add_f32_dpp v74, v74, v74 quad_perm:[1,0,3,2] row_mask:0xf bank_mask:0xf bound_ctrl:1
	v_add_f32_dpp v75, v75, v75 quad_perm:[1,0,3,2] row_mask:0xf bank_mask:0xf bound_ctrl:1
	ds_read_b32 v32, v81 offset:38144
	v_add_f32_dpp v74, v74, v74 quad_perm:[2,3,0,1] row_mask:0xf bank_mask:0xf bound_ctrl:1
	v_add_f32_dpp v75, v75, v75 quad_perm:[2,3,0,1] row_mask:0xf bank_mask:0xf bound_ctrl:1
	ds_read_b32 v33, v82 offset:38144
	v_add_f32_dpp v76, v74, v74 row_half_mirror row_mask:0xf bank_mask:0xf bound_ctrl:1
	v_add_f32_dpp v64, v75, v75 row_half_mirror row_mask:0xf bank_mask:0xf bound_ctrl:1
	v_pk_mul_f32 v[66:67], v[60:61], v[52:53] op_sel_hi:[1,0]
	v_mov_b32_dpp v77, v76 row_ror:8 row_mask:0xf bank_mask:0xf bound_ctrl:1
	v_pk_mul_f32 v[68:69], v[76:77], v[56:57] op_sel:[0,1]
	v_pk_mul_f32 v[70:71], v[76:77], v[58:59] op_sel_hi:[1,0]
	v_pk_mul_f32 v[72:73], v[76:77], v[58:59] op_sel:[0,1]
	v_pk_fma_f32 v[66:67], v[76:77], v[56:57], v[66:67] op_sel_hi:[1,0,1]
	v_pk_fma_f32 v[68:69], v[60:61], v[52:53], v[68:69] op_sel:[0,1,0]
	v_pk_fma_f32 v[70:71], v[60:61], v[54:55], v[70:71] op_sel_hi:[1,0,1]
	v_pk_fma_f32 v[72:73], v[60:61], v[54:55], v[72:73] op_sel:[0,1,0]
	v_pk_fma_f32 v[0:1], v[0:1], v[48:49], v[66:67] op_sel_hi:[1,0,1]
	v_pk_fma_f32 v[2:3], v[2:3], v[48:49], v[68:69] op_sel:[0,1,0]
	v_pk_fma_f32 v[4:5], v[4:5], v[50:51], v[70:71] op_sel_hi:[1,0,1]
	v_pk_fma_f32 v[6:7], v[6:7], v[50:51], v[72:73] op_sel:[0,1,0]
	ds_write_b32 v84, v64 offset:2944
	ds_write_b32 v84, v76 offset:15232
	s_waitcnt lgkmcnt(2)
	v_pk_mul_f32 v[8:9], v[0:1], v[12:13] op_sel_hi:[1,0]
	v_pk_mul_f32 v[10:11], v[0:1], v[16:17] op_sel_hi:[1,0]
	ds_read_b128 v[40:43], v80 offset:39168
	v_pk_fma_f32 v[8:9], v[2:3], v[12:13], v[8:9] op_sel:[0,1,0]
	v_pk_fma_f32 v[10:11], v[2:3], v[16:17], v[10:11] op_sel:[0,1,0]
	ds_read_b128 v[44:47], v80 offset:38400
	v_pk_fma_f32 v[8:9], v[4:5], v[14:15], v[8:9] op_sel_hi:[1,0,1]
	v_pk_fma_f32 v[10:11], v[4:5], v[18:19], v[10:11] op_sel_hi:[1,0,1]
	ds_read_b128 v[48:51], v80 offset:38656
	v_pk_fma_f32 v[8:9], v[6:7], v[14:15], v[8:9] op_sel:[0,1,0]
	v_pk_fma_f32 v[10:11], v[6:7], v[18:19], v[10:11] op_sel:[0,1,0]
	ds_read_b128 v[52:55], v80 offset:38912
	v_add_f32_dpp v74, v9, v8 row_ror:8 row_mask:0xf bank_mask:0xf bound_ctrl:1
	v_add_f32_dpp v75, v11, v10 row_ror:8 row_mask:0xf bank_mask:0xf bound_ctrl:1
	ds_read_b128 v[56:59], v80 offset:39424
	v_add_f32_dpp v74, v74, v74 quad_perm:[1,0,3,2] row_mask:0xf bank_mask:0xf bound_ctrl:1
	v_add_f32_dpp v75, v75, v75 quad_perm:[1,0,3,2] row_mask:0xf bank_mask:0xf bound_ctrl:1
	ds_read_b32 v60, v81 offset:39680
	v_add_f32_dpp v74, v74, v74 quad_perm:[2,3,0,1] row_mask:0xf bank_mask:0xf bound_ctrl:1
	v_add_f32_dpp v75, v75, v75 quad_perm:[2,3,0,1] row_mask:0xf bank_mask:0xf bound_ctrl:1
	ds_read_b32 v61, v82 offset:39680
	v_add_f32_dpp v76, v74, v74 row_half_mirror row_mask:0xf bank_mask:0xf bound_ctrl:1
	v_add_f32_dpp v36, v75, v75 row_half_mirror row_mask:0xf bank_mask:0xf bound_ctrl:1
	v_pk_mul_f32 v[66:67], v[32:33], v[24:25] op_sel_hi:[1,0]
	v_mov_b32_dpp v77, v76 row_ror:8 row_mask:0xf bank_mask:0xf bound_ctrl:1
	v_pk_mul_f32 v[68:69], v[76:77], v[28:29] op_sel:[0,1]
	v_pk_mul_f32 v[70:71], v[76:77], v[30:31] op_sel_hi:[1,0]
	v_pk_mul_f32 v[72:73], v[76:77], v[30:31] op_sel:[0,1]
	v_pk_fma_f32 v[66:67], v[76:77], v[28:29], v[66:67] op_sel_hi:[1,0,1]
	v_pk_fma_f32 v[68:69], v[32:33], v[24:25], v[68:69] op_sel:[0,1,0]
	v_pk_fma_f32 v[70:71], v[32:33], v[26:27], v[70:71] op_sel_hi:[1,0,1]
	v_pk_fma_f32 v[72:73], v[32:33], v[26:27], v[72:73] op_sel:[0,1,0]
	v_pk_fma_f32 v[0:1], v[0:1], v[20:21], v[66:67] op_sel_hi:[1,0,1]
	v_pk_fma_f32 v[2:3], v[2:3], v[20:21], v[68:69] op_sel:[0,1,0]
	v_pk_fma_f32 v[4:5], v[4:5], v[22:23], v[70:71] op_sel_hi:[1,0,1]
	v_pk_fma_f32 v[6:7], v[6:7], v[22:23], v[72:73] op_sel:[0,1,0]
	ds_write_b32 v84, v36 offset:3072
	ds_write_b32 v84, v76 offset:15360
	s_waitcnt lgkmcnt(2)
	v_pk_mul_f32 v[8:9], v[0:1], v[40:41] op_sel_hi:[1,0]
	v_pk_mul_f32 v[10:11], v[0:1], v[44:45] op_sel_hi:[1,0]
	ds_read_b128 v[12:15], v80 offset:40704
	v_pk_fma_f32 v[8:9], v[2:3], v[40:41], v[8:9] op_sel:[0,1,0]
	v_pk_fma_f32 v[10:11], v[2:3], v[44:45], v[10:11] op_sel:[0,1,0]
	ds_read_b128 v[16:19], v80 offset:39936
	v_pk_fma_f32 v[8:9], v[4:5], v[42:43], v[8:9] op_sel_hi:[1,0,1]
	v_pk_fma_f32 v[10:11], v[4:5], v[46:47], v[10:11] op_sel_hi:[1,0,1]
	ds_read_b128 v[20:23], v80 offset:40192
	v_pk_fma_f32 v[8:9], v[6:7], v[42:43], v[8:9] op_sel:[0,1,0]
	v_pk_fma_f32 v[10:11], v[6:7], v[46:47], v[10:11] op_sel:[0,1,0]
	ds_read_b128 v[24:27], v80 offset:40448
	v_add_f32_dpp v74, v9, v8 row_ror:8 row_mask:0xf bank_mask:0xf bound_ctrl:1
	v_add_f32_dpp v75, v11, v10 row_ror:8 row_mask:0xf bank_mask:0xf bound_ctrl:1
	ds_read_b128 v[28:31], v80 offset:40960
	v_add_f32_dpp v74, v74, v74 quad_perm:[1,0,3,2] row_mask:0xf bank_mask:0xf bound_ctrl:1
	v_add_f32_dpp v75, v75, v75 quad_perm:[1,0,3,2] row_mask:0xf bank_mask:0xf bound_ctrl:1
	ds_read_b32 v32, v81 offset:41216
	v_add_f32_dpp v74, v74, v74 quad_perm:[2,3,0,1] row_mask:0xf bank_mask:0xf bound_ctrl:1
	v_add_f32_dpp v75, v75, v75 quad_perm:[2,3,0,1] row_mask:0xf bank_mask:0xf bound_ctrl:1
	ds_read_b32 v33, v82 offset:41216
	v_add_f32_dpp v76, v74, v74 row_half_mirror row_mask:0xf bank_mask:0xf bound_ctrl:1
	v_add_f32_dpp v64, v75, v75 row_half_mirror row_mask:0xf bank_mask:0xf bound_ctrl:1
	v_pk_mul_f32 v[66:67], v[60:61], v[52:53] op_sel_hi:[1,0]
	v_mov_b32_dpp v77, v76 row_ror:8 row_mask:0xf bank_mask:0xf bound_ctrl:1
	v_pk_mul_f32 v[68:69], v[76:77], v[56:57] op_sel:[0,1]
	v_pk_mul_f32 v[70:71], v[76:77], v[58:59] op_sel_hi:[1,0]
	v_pk_mul_f32 v[72:73], v[76:77], v[58:59] op_sel:[0,1]
	v_pk_fma_f32 v[66:67], v[76:77], v[56:57], v[66:67] op_sel_hi:[1,0,1]
	v_pk_fma_f32 v[68:69], v[60:61], v[52:53], v[68:69] op_sel:[0,1,0]
	v_pk_fma_f32 v[70:71], v[60:61], v[54:55], v[70:71] op_sel_hi:[1,0,1]
	v_pk_fma_f32 v[72:73], v[60:61], v[54:55], v[72:73] op_sel:[0,1,0]
	v_pk_fma_f32 v[0:1], v[0:1], v[48:49], v[66:67] op_sel_hi:[1,0,1]
	v_pk_fma_f32 v[2:3], v[2:3], v[48:49], v[68:69] op_sel:[0,1,0]
	v_pk_fma_f32 v[4:5], v[4:5], v[50:51], v[70:71] op_sel_hi:[1,0,1]
	v_pk_fma_f32 v[6:7], v[6:7], v[50:51], v[72:73] op_sel:[0,1,0]
	ds_write_b32 v84, v64 offset:3200
	ds_write_b32 v84, v76 offset:15488
	s_waitcnt lgkmcnt(2)
	v_pk_mul_f32 v[8:9], v[0:1], v[12:13] op_sel_hi:[1,0]
	v_pk_mul_f32 v[10:11], v[0:1], v[16:17] op_sel_hi:[1,0]
	ds_read_b128 v[40:43], v80 offset:42240
	v_pk_fma_f32 v[8:9], v[2:3], v[12:13], v[8:9] op_sel:[0,1,0]
	v_pk_fma_f32 v[10:11], v[2:3], v[16:17], v[10:11] op_sel:[0,1,0]
	ds_read_b128 v[44:47], v80 offset:41472
	v_pk_fma_f32 v[8:9], v[4:5], v[14:15], v[8:9] op_sel_hi:[1,0,1]
	v_pk_fma_f32 v[10:11], v[4:5], v[18:19], v[10:11] op_sel_hi:[1,0,1]
	ds_read_b128 v[48:51], v80 offset:41728
	v_pk_fma_f32 v[8:9], v[6:7], v[14:15], v[8:9] op_sel:[0,1,0]
	v_pk_fma_f32 v[10:11], v[6:7], v[18:19], v[10:11] op_sel:[0,1,0]
	ds_read_b128 v[52:55], v80 offset:41984
	v_add_f32_dpp v74, v9, v8 row_ror:8 row_mask:0xf bank_mask:0xf bound_ctrl:1
	v_add_f32_dpp v75, v11, v10 row_ror:8 row_mask:0xf bank_mask:0xf bound_ctrl:1
	ds_read_b128 v[56:59], v80 offset:42496
	v_add_f32_dpp v74, v74, v74 quad_perm:[1,0,3,2] row_mask:0xf bank_mask:0xf bound_ctrl:1
	v_add_f32_dpp v75, v75, v75 quad_perm:[1,0,3,2] row_mask:0xf bank_mask:0xf bound_ctrl:1
	ds_read_b32 v60, v81 offset:42752
	v_add_f32_dpp v74, v74, v74 quad_perm:[2,3,0,1] row_mask:0xf bank_mask:0xf bound_ctrl:1
	v_add_f32_dpp v75, v75, v75 quad_perm:[2,3,0,1] row_mask:0xf bank_mask:0xf bound_ctrl:1
	ds_read_b32 v61, v82 offset:42752
	v_add_f32_dpp v76, v74, v74 row_half_mirror row_mask:0xf bank_mask:0xf bound_ctrl:1
	v_add_f32_dpp v36, v75, v75 row_half_mirror row_mask:0xf bank_mask:0xf bound_ctrl:1
	v_pk_mul_f32 v[66:67], v[32:33], v[24:25] op_sel_hi:[1,0]
	v_mov_b32_dpp v77, v76 row_ror:8 row_mask:0xf bank_mask:0xf bound_ctrl:1
	v_pk_mul_f32 v[68:69], v[76:77], v[28:29] op_sel:[0,1]
	v_pk_mul_f32 v[70:71], v[76:77], v[30:31] op_sel_hi:[1,0]
	v_pk_mul_f32 v[72:73], v[76:77], v[30:31] op_sel:[0,1]
	v_pk_fma_f32 v[66:67], v[76:77], v[28:29], v[66:67] op_sel_hi:[1,0,1]
	v_pk_fma_f32 v[68:69], v[32:33], v[24:25], v[68:69] op_sel:[0,1,0]
	v_pk_fma_f32 v[70:71], v[32:33], v[26:27], v[70:71] op_sel_hi:[1,0,1]
	v_pk_fma_f32 v[72:73], v[32:33], v[26:27], v[72:73] op_sel:[0,1,0]
	v_pk_fma_f32 v[0:1], v[0:1], v[20:21], v[66:67] op_sel_hi:[1,0,1]
	v_pk_fma_f32 v[2:3], v[2:3], v[20:21], v[68:69] op_sel:[0,1,0]
	v_pk_fma_f32 v[4:5], v[4:5], v[22:23], v[70:71] op_sel_hi:[1,0,1]
	v_pk_fma_f32 v[6:7], v[6:7], v[22:23], v[72:73] op_sel:[0,1,0]
	ds_write_b32 v84, v36 offset:3328
	ds_write_b32 v84, v76 offset:15616
	s_waitcnt lgkmcnt(2)
	v_pk_mul_f32 v[8:9], v[0:1], v[40:41] op_sel_hi:[1,0]
	v_pk_mul_f32 v[10:11], v[0:1], v[44:45] op_sel_hi:[1,0]
	ds_read_b128 v[12:15], v80 offset:43776
	v_pk_fma_f32 v[8:9], v[2:3], v[40:41], v[8:9] op_sel:[0,1,0]
	v_pk_fma_f32 v[10:11], v[2:3], v[44:45], v[10:11] op_sel:[0,1,0]
	ds_read_b128 v[16:19], v80 offset:43008
	v_pk_fma_f32 v[8:9], v[4:5], v[42:43], v[8:9] op_sel_hi:[1,0,1]
	v_pk_fma_f32 v[10:11], v[4:5], v[46:47], v[10:11] op_sel_hi:[1,0,1]
	ds_read_b128 v[20:23], v80 offset:43264
	v_pk_fma_f32 v[8:9], v[6:7], v[42:43], v[8:9] op_sel:[0,1,0]
	v_pk_fma_f32 v[10:11], v[6:7], v[46:47], v[10:11] op_sel:[0,1,0]
	ds_read_b128 v[24:27], v80 offset:43520
	v_add_f32_dpp v74, v9, v8 row_ror:8 row_mask:0xf bank_mask:0xf bound_ctrl:1
	v_add_f32_dpp v75, v11, v10 row_ror:8 row_mask:0xf bank_mask:0xf bound_ctrl:1
	ds_read_b128 v[28:31], v80 offset:44032
	v_add_f32_dpp v74, v74, v74 quad_perm:[1,0,3,2] row_mask:0xf bank_mask:0xf bound_ctrl:1
	v_add_f32_dpp v75, v75, v75 quad_perm:[1,0,3,2] row_mask:0xf bank_mask:0xf bound_ctrl:1
	ds_read_b32 v32, v81 offset:44288
	v_add_f32_dpp v74, v74, v74 quad_perm:[2,3,0,1] row_mask:0xf bank_mask:0xf bound_ctrl:1
	v_add_f32_dpp v75, v75, v75 quad_perm:[2,3,0,1] row_mask:0xf bank_mask:0xf bound_ctrl:1
	ds_read_b32 v33, v82 offset:44288
	v_add_f32_dpp v76, v74, v74 row_half_mirror row_mask:0xf bank_mask:0xf bound_ctrl:1
	v_add_f32_dpp v64, v75, v75 row_half_mirror row_mask:0xf bank_mask:0xf bound_ctrl:1
	v_pk_mul_f32 v[66:67], v[60:61], v[52:53] op_sel_hi:[1,0]
	v_mov_b32_dpp v77, v76 row_ror:8 row_mask:0xf bank_mask:0xf bound_ctrl:1
	v_pk_mul_f32 v[68:69], v[76:77], v[56:57] op_sel:[0,1]
	v_pk_mul_f32 v[70:71], v[76:77], v[58:59] op_sel_hi:[1,0]
	v_pk_mul_f32 v[72:73], v[76:77], v[58:59] op_sel:[0,1]
	v_pk_fma_f32 v[66:67], v[76:77], v[56:57], v[66:67] op_sel_hi:[1,0,1]
	v_pk_fma_f32 v[68:69], v[60:61], v[52:53], v[68:69] op_sel:[0,1,0]
	v_pk_fma_f32 v[70:71], v[60:61], v[54:55], v[70:71] op_sel_hi:[1,0,1]
	v_pk_fma_f32 v[72:73], v[60:61], v[54:55], v[72:73] op_sel:[0,1,0]
	v_pk_fma_f32 v[0:1], v[0:1], v[48:49], v[66:67] op_sel_hi:[1,0,1]
	v_pk_fma_f32 v[2:3], v[2:3], v[48:49], v[68:69] op_sel:[0,1,0]
	v_pk_fma_f32 v[4:5], v[4:5], v[50:51], v[70:71] op_sel_hi:[1,0,1]
	v_pk_fma_f32 v[6:7], v[6:7], v[50:51], v[72:73] op_sel:[0,1,0]
	ds_write_b32 v84, v64 offset:3456
	ds_write_b32 v84, v76 offset:15744
	s_waitcnt lgkmcnt(2)
	v_pk_mul_f32 v[8:9], v[0:1], v[12:13] op_sel_hi:[1,0]
	v_pk_mul_f32 v[10:11], v[0:1], v[16:17] op_sel_hi:[1,0]
	ds_read_b128 v[40:43], v80 offset:45312
	v_pk_fma_f32 v[8:9], v[2:3], v[12:13], v[8:9] op_sel:[0,1,0]
	v_pk_fma_f32 v[10:11], v[2:3], v[16:17], v[10:11] op_sel:[0,1,0]
	ds_read_b128 v[44:47], v80 offset:44544
	v_pk_fma_f32 v[8:9], v[4:5], v[14:15], v[8:9] op_sel_hi:[1,0,1]
	v_pk_fma_f32 v[10:11], v[4:5], v[18:19], v[10:11] op_sel_hi:[1,0,1]
	ds_read_b128 v[48:51], v80 offset:44800
	v_pk_fma_f32 v[8:9], v[6:7], v[14:15], v[8:9] op_sel:[0,1,0]
	v_pk_fma_f32 v[10:11], v[6:7], v[18:19], v[10:11] op_sel:[0,1,0]
	ds_read_b128 v[52:55], v80 offset:45056
	v_add_f32_dpp v74, v9, v8 row_ror:8 row_mask:0xf bank_mask:0xf bound_ctrl:1
	v_add_f32_dpp v75, v11, v10 row_ror:8 row_mask:0xf bank_mask:0xf bound_ctrl:1
	ds_read_b128 v[56:59], v80 offset:45568
	v_add_f32_dpp v74, v74, v74 quad_perm:[1,0,3,2] row_mask:0xf bank_mask:0xf bound_ctrl:1
	v_add_f32_dpp v75, v75, v75 quad_perm:[1,0,3,2] row_mask:0xf bank_mask:0xf bound_ctrl:1
	ds_read_b32 v60, v81 offset:45824
	v_add_f32_dpp v74, v74, v74 quad_perm:[2,3,0,1] row_mask:0xf bank_mask:0xf bound_ctrl:1
	v_add_f32_dpp v75, v75, v75 quad_perm:[2,3,0,1] row_mask:0xf bank_mask:0xf bound_ctrl:1
	ds_read_b32 v61, v82 offset:45824
	v_add_f32_dpp v76, v74, v74 row_half_mirror row_mask:0xf bank_mask:0xf bound_ctrl:1
	v_add_f32_dpp v36, v75, v75 row_half_mirror row_mask:0xf bank_mask:0xf bound_ctrl:1
	v_pk_mul_f32 v[66:67], v[32:33], v[24:25] op_sel_hi:[1,0]
	v_mov_b32_dpp v77, v76 row_ror:8 row_mask:0xf bank_mask:0xf bound_ctrl:1
	v_pk_mul_f32 v[68:69], v[76:77], v[28:29] op_sel:[0,1]
	v_pk_mul_f32 v[70:71], v[76:77], v[30:31] op_sel_hi:[1,0]
	v_pk_mul_f32 v[72:73], v[76:77], v[30:31] op_sel:[0,1]
	v_pk_fma_f32 v[66:67], v[76:77], v[28:29], v[66:67] op_sel_hi:[1,0,1]
	v_pk_fma_f32 v[68:69], v[32:33], v[24:25], v[68:69] op_sel:[0,1,0]
	v_pk_fma_f32 v[70:71], v[32:33], v[26:27], v[70:71] op_sel_hi:[1,0,1]
	v_pk_fma_f32 v[72:73], v[32:33], v[26:27], v[72:73] op_sel:[0,1,0]
	v_pk_fma_f32 v[0:1], v[0:1], v[20:21], v[66:67] op_sel_hi:[1,0,1]
	v_pk_fma_f32 v[2:3], v[2:3], v[20:21], v[68:69] op_sel:[0,1,0]
	v_pk_fma_f32 v[4:5], v[4:5], v[22:23], v[70:71] op_sel_hi:[1,0,1]
	v_pk_fma_f32 v[6:7], v[6:7], v[22:23], v[72:73] op_sel:[0,1,0]
	ds_write_b32 v84, v36 offset:3584
	ds_write_b32 v84, v76 offset:15872
	s_waitcnt lgkmcnt(2)
	v_pk_mul_f32 v[8:9], v[0:1], v[40:41] op_sel_hi:[1,0]
	v_pk_mul_f32 v[10:11], v[0:1], v[44:45] op_sel_hi:[1,0]
	ds_read_b128 v[12:15], v80 offset:46848
	v_pk_fma_f32 v[8:9], v[2:3], v[40:41], v[8:9] op_sel:[0,1,0]
	v_pk_fma_f32 v[10:11], v[2:3], v[44:45], v[10:11] op_sel:[0,1,0]
	ds_read_b128 v[16:19], v80 offset:46080
	v_pk_fma_f32 v[8:9], v[4:5], v[42:43], v[8:9] op_sel_hi:[1,0,1]
	v_pk_fma_f32 v[10:11], v[4:5], v[46:47], v[10:11] op_sel_hi:[1,0,1]
	ds_read_b128 v[20:23], v80 offset:46336
	v_pk_fma_f32 v[8:9], v[6:7], v[42:43], v[8:9] op_sel:[0,1,0]
	v_pk_fma_f32 v[10:11], v[6:7], v[46:47], v[10:11] op_sel:[0,1,0]
	ds_read_b128 v[24:27], v80 offset:46592
	v_add_f32_dpp v74, v9, v8 row_ror:8 row_mask:0xf bank_mask:0xf bound_ctrl:1
	v_add_f32_dpp v75, v11, v10 row_ror:8 row_mask:0xf bank_mask:0xf bound_ctrl:1
	ds_read_b128 v[28:31], v80 offset:47104
	v_add_f32_dpp v74, v74, v74 quad_perm:[1,0,3,2] row_mask:0xf bank_mask:0xf bound_ctrl:1
	v_add_f32_dpp v75, v75, v75 quad_perm:[1,0,3,2] row_mask:0xf bank_mask:0xf bound_ctrl:1
	ds_read_b32 v32, v81 offset:47360
	v_add_f32_dpp v74, v74, v74 quad_perm:[2,3,0,1] row_mask:0xf bank_mask:0xf bound_ctrl:1
	v_add_f32_dpp v75, v75, v75 quad_perm:[2,3,0,1] row_mask:0xf bank_mask:0xf bound_ctrl:1
	ds_read_b32 v33, v82 offset:47360
	v_add_f32_dpp v76, v74, v74 row_half_mirror row_mask:0xf bank_mask:0xf bound_ctrl:1
	v_add_f32_dpp v64, v75, v75 row_half_mirror row_mask:0xf bank_mask:0xf bound_ctrl:1
	v_pk_mul_f32 v[66:67], v[60:61], v[52:53] op_sel_hi:[1,0]
	v_mov_b32_dpp v77, v76 row_ror:8 row_mask:0xf bank_mask:0xf bound_ctrl:1
	v_pk_mul_f32 v[68:69], v[76:77], v[56:57] op_sel:[0,1]
	v_pk_mul_f32 v[70:71], v[76:77], v[58:59] op_sel_hi:[1,0]
	v_pk_mul_f32 v[72:73], v[76:77], v[58:59] op_sel:[0,1]
	v_pk_fma_f32 v[66:67], v[76:77], v[56:57], v[66:67] op_sel_hi:[1,0,1]
	v_pk_fma_f32 v[68:69], v[60:61], v[52:53], v[68:69] op_sel:[0,1,0]
	v_pk_fma_f32 v[70:71], v[60:61], v[54:55], v[70:71] op_sel_hi:[1,0,1]
	v_pk_fma_f32 v[72:73], v[60:61], v[54:55], v[72:73] op_sel:[0,1,0]
	v_pk_fma_f32 v[0:1], v[0:1], v[48:49], v[66:67] op_sel_hi:[1,0,1]
	v_pk_fma_f32 v[2:3], v[2:3], v[48:49], v[68:69] op_sel:[0,1,0]
	v_pk_fma_f32 v[4:5], v[4:5], v[50:51], v[70:71] op_sel_hi:[1,0,1]
	v_pk_fma_f32 v[6:7], v[6:7], v[50:51], v[72:73] op_sel:[0,1,0]
	ds_write_b32 v84, v64 offset:3712
	ds_write_b32 v84, v76 offset:16000
	s_waitcnt lgkmcnt(2)
	v_pk_mul_f32 v[8:9], v[0:1], v[12:13] op_sel_hi:[1,0]
	v_pk_mul_f32 v[10:11], v[0:1], v[16:17] op_sel_hi:[1,0]
	ds_read_b128 v[40:43], v80 offset:48384
	v_pk_fma_f32 v[8:9], v[2:3], v[12:13], v[8:9] op_sel:[0,1,0]
	v_pk_fma_f32 v[10:11], v[2:3], v[16:17], v[10:11] op_sel:[0,1,0]
	ds_read_b128 v[44:47], v80 offset:47616
	v_pk_fma_f32 v[8:9], v[4:5], v[14:15], v[8:9] op_sel_hi:[1,0,1]
	v_pk_fma_f32 v[10:11], v[4:5], v[18:19], v[10:11] op_sel_hi:[1,0,1]
	ds_read_b128 v[48:51], v80 offset:47872
	v_pk_fma_f32 v[8:9], v[6:7], v[14:15], v[8:9] op_sel:[0,1,0]
	v_pk_fma_f32 v[10:11], v[6:7], v[18:19], v[10:11] op_sel:[0,1,0]
	ds_read_b128 v[52:55], v80 offset:48128
	v_add_f32_dpp v74, v9, v8 row_ror:8 row_mask:0xf bank_mask:0xf bound_ctrl:1
	v_add_f32_dpp v75, v11, v10 row_ror:8 row_mask:0xf bank_mask:0xf bound_ctrl:1
	ds_read_b128 v[56:59], v80 offset:48640
	v_add_f32_dpp v74, v74, v74 quad_perm:[1,0,3,2] row_mask:0xf bank_mask:0xf bound_ctrl:1
	v_add_f32_dpp v75, v75, v75 quad_perm:[1,0,3,2] row_mask:0xf bank_mask:0xf bound_ctrl:1
	ds_read_b32 v60, v81 offset:48896
	v_add_f32_dpp v74, v74, v74 quad_perm:[2,3,0,1] row_mask:0xf bank_mask:0xf bound_ctrl:1
	v_add_f32_dpp v75, v75, v75 quad_perm:[2,3,0,1] row_mask:0xf bank_mask:0xf bound_ctrl:1
	ds_read_b32 v61, v82 offset:48896
	v_add_f32_dpp v76, v74, v74 row_half_mirror row_mask:0xf bank_mask:0xf bound_ctrl:1
	v_add_f32_dpp v36, v75, v75 row_half_mirror row_mask:0xf bank_mask:0xf bound_ctrl:1
	v_pk_mul_f32 v[66:67], v[32:33], v[24:25] op_sel_hi:[1,0]
	v_mov_b32_dpp v77, v76 row_ror:8 row_mask:0xf bank_mask:0xf bound_ctrl:1
	v_pk_mul_f32 v[68:69], v[76:77], v[28:29] op_sel:[0,1]
	v_pk_mul_f32 v[70:71], v[76:77], v[30:31] op_sel_hi:[1,0]
	v_pk_mul_f32 v[72:73], v[76:77], v[30:31] op_sel:[0,1]
	v_pk_fma_f32 v[66:67], v[76:77], v[28:29], v[66:67] op_sel_hi:[1,0,1]
	v_pk_fma_f32 v[68:69], v[32:33], v[24:25], v[68:69] op_sel:[0,1,0]
	v_pk_fma_f32 v[70:71], v[32:33], v[26:27], v[70:71] op_sel_hi:[1,0,1]
	v_pk_fma_f32 v[72:73], v[32:33], v[26:27], v[72:73] op_sel:[0,1,0]
	v_pk_fma_f32 v[0:1], v[0:1], v[20:21], v[66:67] op_sel_hi:[1,0,1]
	v_pk_fma_f32 v[2:3], v[2:3], v[20:21], v[68:69] op_sel:[0,1,0]
	v_pk_fma_f32 v[4:5], v[4:5], v[22:23], v[70:71] op_sel_hi:[1,0,1]
	v_pk_fma_f32 v[6:7], v[6:7], v[22:23], v[72:73] op_sel:[0,1,0]
	ds_write_b32 v84, v36 offset:3840
	ds_write_b32 v84, v76 offset:16128
	s_waitcnt lgkmcnt(2)
	v_pk_mul_f32 v[8:9], v[0:1], v[40:41] op_sel_hi:[1,0]
	v_pk_mul_f32 v[10:11], v[0:1], v[44:45] op_sel_hi:[1,0]
	v_pk_fma_f32 v[8:9], v[2:3], v[40:41], v[8:9] op_sel:[0,1,0]
	v_pk_fma_f32 v[10:11], v[2:3], v[44:45], v[10:11] op_sel:[0,1,0]
	v_pk_fma_f32 v[8:9], v[4:5], v[42:43], v[8:9] op_sel_hi:[1,0,1]
	v_pk_fma_f32 v[10:11], v[4:5], v[46:47], v[10:11] op_sel_hi:[1,0,1]
	v_pk_fma_f32 v[8:9], v[6:7], v[42:43], v[8:9] op_sel:[0,1,0]
	v_pk_fma_f32 v[10:11], v[6:7], v[46:47], v[10:11] op_sel:[0,1,0]
	s_nop 0
	v_add_f32_dpp v74, v9, v8 row_ror:8 row_mask:0xf bank_mask:0xf bound_ctrl:1
	v_add_f32_dpp v75, v11, v10 row_ror:8 row_mask:0xf bank_mask:0xf bound_ctrl:1
	s_nop 0
	v_add_f32_dpp v74, v74, v74 quad_perm:[1,0,3,2] row_mask:0xf bank_mask:0xf bound_ctrl:1
	v_add_f32_dpp v75, v75, v75 quad_perm:[1,0,3,2] row_mask:0xf bank_mask:0xf bound_ctrl:1
	s_nop 0
	v_add_f32_dpp v74, v74, v74 quad_perm:[2,3,0,1] row_mask:0xf bank_mask:0xf bound_ctrl:1
	v_add_f32_dpp v75, v75, v75 quad_perm:[2,3,0,1] row_mask:0xf bank_mask:0xf bound_ctrl:1
	s_nop 0
	v_add_f32_dpp v76, v74, v74 row_half_mirror row_mask:0xf bank_mask:0xf bound_ctrl:1
	v_add_f32_dpp v64, v75, v75 row_half_mirror row_mask:0xf bank_mask:0xf bound_ctrl:1
	v_pk_mul_f32 v[66:67], v[60:61], v[52:53] op_sel_hi:[1,0]
	v_mov_b32_dpp v77, v76 row_ror:8 row_mask:0xf bank_mask:0xf bound_ctrl:1
	v_pk_mul_f32 v[68:69], v[76:77], v[56:57] op_sel:[0,1]
	v_pk_mul_f32 v[70:71], v[76:77], v[58:59] op_sel_hi:[1,0]
	v_pk_mul_f32 v[72:73], v[76:77], v[58:59] op_sel:[0,1]
	v_pk_fma_f32 v[66:67], v[76:77], v[56:57], v[66:67] op_sel_hi:[1,0,1]
	v_pk_fma_f32 v[68:69], v[60:61], v[52:53], v[68:69] op_sel:[0,1,0]
	v_pk_fma_f32 v[70:71], v[60:61], v[54:55], v[70:71] op_sel_hi:[1,0,1]
	v_pk_fma_f32 v[72:73], v[60:61], v[54:55], v[72:73] op_sel:[0,1,0]
	v_pk_fma_f32 v[0:1], v[0:1], v[48:49], v[66:67] op_sel_hi:[1,0,1]
	v_pk_fma_f32 v[2:3], v[2:3], v[48:49], v[68:69] op_sel:[0,1,0]
	v_pk_fma_f32 v[4:5], v[4:5], v[50:51], v[70:71] op_sel_hi:[1,0,1]
	v_pk_fma_f32 v[6:7], v[6:7], v[50:51], v[72:73] op_sel:[0,1,0]
	ds_write_b32 v84, v64 offset:3968
	ds_write_b32 v84, v76 offset:16256
